# half of the weight conversion (FFN2 gate/up/down + W_out of each layer) moved out of phase 0 into the idle half of the grid during the last round of that layer's W_in GEMM; write-through GEMM epilogue
# speedup vs baseline: 1.0103x; 1.0020x over previous
; __device__ __forceinline__ int opaque_tid() { int t = threadIdx.x; asm volatile("" : "+v"(t)); return t; }
; #define CVT_LOAD(tile_) do { const int k0_ = ((tile_) / ntn) << 7, n0_ = ((tile_) % ntn) << 6; \
;         _Pragma("unroll") for (int pp = 0; pp < 4; ++pp) pv[pp] = *(const float4*)(src + (size_t)(k0_ + lk + 32 * pp) * N + n0_ + ln4); } while (0)
; __device__ __forceinline__ void convT_job(const float* __restrict__ src, bf16_t* __restrict__ dst, int K, int N, int mode, float* t) {
;     const int tid = opaque_tid(), ntn = N >> 6, ntiles = (K >> 7) * ntn;
;     const int lk = tid >> 4, ln4 = (tid & 15) * 4;
;     float4 pv[4];
;     ...
;     int tile = blockIdx.x;
;     if (tile < ntiles) CVT_LOAD(tile);
; __device__ __forceinline__ void phase_convert(const Params& p, unsigned char* smem) {
;     ...
;     for (int l = 0; l < 2; ++l) {
;         for (int f = 0; f < 2; ++f) {
;             const size_t wo = (size_t)(l * 2 + f) * 2048 * 5632;
;             bf16_t* gu = (bf16_t*)(p.ws + OFF_GU + (size_t)(l * 2 + f) * SZ_GU);
;             convT_job(p.in[3] + wo, gu, 2048, 5632, 1, t);
.LBB0_543:
	v_readlane_b32 s57, v255, 23
	s_mov_b32 s56, 0x1c488000
	s_barrier
	s_cmp_lt_u32 s60, 128
	s_cbranch_scc1 .Ldf_end
	v_readlane_b32 s53, v255, 33
	v_lshrrev_b32_e32 v6, 6, v234
	v_and_b32_e32 v25, 63, v234
	v_lshrrev_b32_e32 v26, 3, v234
	v_readfirstlane_b32 s46, v6
	v_and_b32_e32 v27, 7, v234
	v_readlane_b32 s54, v255, 28
	v_readlane_b32 s55, v255, 29
	s_lshl_b32 s46, s46, 12
	v_lshrrev_b32_e32 v28, 2, v26
	v_xor_b32_e32 v28, v28, v27
	v_lshlrev_b32_e32 v28, 4, v28
	v_and_b32_e32 v29, 3, v26
	v_lshl_or_b32 v28, v29, 2, v28
	v_lshl_or_b32 v4, v27, 12, v28
	v_lshrrev_b32_e32 v30, 4, v25
	v_lshl_add_u32 v30, v6, 4, v30
	v_and_b32_e32 v31, 15, v25
	v_xor_b32_e32 v31, v31, v6
	v_lshlrev_b32_e32 v31, 4, v31
	v_lshlrev_b32_e32 v27, 5, v27
	s_sub_u32 s40, s60, 128
	s_cmp_lt_u32 s40, 1408
	s_cbranch_scc0 .Ldf_dgate_skip
	s_mul_i32 s0, s53, 2
	s_add_u32 s0, s0, 1
	s_mul_hi_u32 s1, s0, 0x2c00000
	s_mul_i32 s2, s0, 0x2c00000
	s_add_u32 s50, s70, s2
	s_addc_u32 s51, s71, s1
	s_mul_i32 s52, s0, 0x2c00000
	s_add_u32 s52, s52, 0x8000
	v_mov_b32_e32 v29, 0x5800
	v_mov_b32_e32 v28, 0x1000
	v_mad_u32_u24 v0, v30, v29, v31
	v_mad_u32_u24 v5, v26, v28, v27
	v_add_u32_e32 v1, 0x16000, v0
	v_add_u32_e32 v2, 0x2c000, v0
	v_add_u32_e32 v3, 0x42000, v0
	s_barrier
	s_mov_b32 s41, 0
	s_mov_b32 s47, s40
	s_mov_b32 s48, s46
	s_mul_hi_u32 s0, s47, 0x2e8ba3
	s_mul_i32 s1, s0, 1408
	s_sub_u32 s1, s47, s1
	s_mul_hi_u32 s2, s1, 0x2e8ba2f
	s_mul_i32 s8, s2, 88
	s_sub_u32 s8, s1, s8
	s_mul_i32 s9, s0, 0x2c00000
	s_mul_i32 s28, s2, 0x2c0000
	s_add_u32 s9, s9, s28
	s_lshl_b32 s8, s8, 8
	s_add_u32 s9, s9, s8
	s_add_u32 s42, s50, s9
	s_addc_u32 s43, s51, 0
	s_mov_b32 m0, s48
	s_add_u32 s49, s48, 0x400
	global_load_lds_dwordx4 v0, s[42:43]
	s_mov_b32 m0, s49
	s_add_u32 s49, s48, 0x800
	global_load_lds_dwordx4 v1, s[42:43]
	s_mov_b32 m0, s49
	s_add_u32 s49, s48, 0xc00
	global_load_lds_dwordx4 v2, s[42:43]
	s_mov_b32 m0, s49
	s_nop 0
	global_load_lds_dwordx4 v3, s[42:43]
	global_load_dword v24, v173, s[70:71]
	global_load_dword v24, v173, s[70:71]
	s_add_u32 s47, s40, 128
	s_add_u32 s48, s46, 0x8000
	s_cmp_lt_u32 s47, 1408
	s_cbranch_scc0 .Ldf_dgate_pd1
	s_mul_hi_u32 s0, s47, 0x2e8ba3
	s_mul_i32 s1, s0, 1408
	s_sub_u32 s1, s47, s1
	s_mul_hi_u32 s2, s1, 0x2e8ba2f
	s_mul_i32 s8, s2, 88
	s_sub_u32 s8, s1, s8
	s_mul_i32 s9, s0, 0x2c00000
	s_mul_i32 s28, s2, 0x2c0000
	s_add_u32 s9, s9, s28
	s_lshl_b32 s8, s8, 8
	s_add_u32 s9, s9, s8
	s_add_u32 s42, s50, s9
	s_addc_u32 s43, s51, 0
	s_mov_b32 m0, s48
	s_add_u32 s49, s48, 0x400
	global_load_lds_dwordx4 v0, s[42:43]
	s_mov_b32 m0, s49
	s_add_u32 s49, s48, 0x800
	global_load_lds_dwordx4 v1, s[42:43]
	s_mov_b32 m0, s49
	s_add_u32 s49, s48, 0xc00
	global_load_lds_dwordx4 v2, s[42:43]
	s_mov_b32 m0, s49
	s_nop 0
	global_load_lds_dwordx4 v3, s[42:43]
	s_branch .Ldf_dgate_pj1

; #define CVT_LOAD(tile_) do { const int k0_ = ((tile_) / ntn) << 7, n0_ = ((tile_) % ntn) << 6; \
;         _Pragma("unroll") for (int pp = 0; pp < 4; ++pp) pv[pp] = *(const float4*)(src + (size_t)(k0_ + lk + 32 * pp) * N + n0_ + ln4); } while (0)
; __device__ __forceinline__ void convT_job(const float* __restrict__ src, bf16_t* __restrict__ dst, int K, int N, int mode, float* t) {
;     ...
;     int tile = blockIdx.x;
;     if (tile < ntiles) CVT_LOAD(tile);
;     ...
;         if (tile + (int)gridDim.x < ntiles) CVT_LOAD(tile + (int)gridDim.x);
.Ldf_dgate_pj1:
	global_load_dword v24, v173, s[70:71]
	global_load_dword v24, v173, s[70:71]
	s_add_u32 s47, s40, 256
	s_add_u32 s48, s46, 0x10000
	s_cmp_lt_u32 s47, 1408
	s_cbranch_scc0 .Ldf_dgate_pd2
	s_mul_hi_u32 s0, s47, 0x2e8ba3
	s_mul_i32 s1, s0, 1408
	s_sub_u32 s1, s47, s1
	s_mul_hi_u32 s2, s1, 0x2e8ba2f
	s_mul_i32 s8, s2, 88
	s_sub_u32 s8, s1, s8
	s_mul_i32 s9, s0, 0x2c00000
	s_mul_i32 s28, s2, 0x2c0000
	s_add_u32 s9, s9, s28
	s_lshl_b32 s8, s8, 8
	s_add_u32 s9, s9, s8
	s_add_u32 s42, s50, s9
	s_addc_u32 s43, s51, 0
	s_mov_b32 m0, s48
	s_add_u32 s49, s48, 0x400
	global_load_lds_dwordx4 v0, s[42:43]
	s_mov_b32 m0, s49
	s_add_u32 s49, s48, 0x800
	global_load_lds_dwordx4 v1, s[42:43]
	s_mov_b32 m0, s49
	s_add_u32 s49, s48, 0xc00
	global_load_lds_dwordx4 v2, s[42:43]
	s_mov_b32 m0, s49
	s_nop 0
	global_load_lds_dwordx4 v3, s[42:43]
	s_branch .Ldf_dgate_pj2

; __device__ __forceinline__ void lds_barrier() { asm volatile("s_waitcnt lgkmcnt(0)" ::: "memory"); __builtin_amdgcn_s_barrier(); asm volatile("" ::: "memory"); }
; #define CVT_LOAD(tile_) do { const int k0_ = ((tile_) / ntn) << 7, n0_ = ((tile_) % ntn) << 6; \
;         _Pragma("unroll") for (int pp = 0; pp < 4; ++pp) pv[pp] = *(const float4*)(src + (size_t)(k0_ + lk + 32 * pp) * N + n0_ + ln4); } while (0)
; __device__ __forceinline__ void convT_job(const float* __restrict__ src, bf16_t* __restrict__ dst, int K, int N, int mode, float* t) {
;     ...
;     for (; tile < ntiles; tile += gridDim.x) {
;         const int k0 = (tile / ntn) << 7, n0 = (tile % ntn) << 6;
; #pragma unroll
;         for (int pp = 0; pp < 4; ++pp) { const int k = lk + 32 * pp; t[k * 65 + ln4] = pv[pp].x; t[k * 65 + ln4 + 1] = pv[pp].y; t[k * 65 + ln4 + 2] = pv[pp].z; t[k * 65 + ln4 + 3] = pv[pp].w; }
;         if (tile + (int)gridDim.x < ntiles) CVT_LOAD(tile + (int)gridDim.x);
;         lds_barrier();
.Ldf_dgate_loop:
	s_waitcnt vmcnt(14)
	s_barrier
	s_add_u32 s47, s40, 384
	s_add_u32 s48, s41, 0x18000
	s_and_b32 s48, s48, 0x1ffff
	s_add_u32 s48, s48, s46
	s_cmp_lt_u32 s47, 1408
	s_cbranch_scc0 .Ldf_dgate_ld
	s_mul_hi_u32 s0, s47, 0x2e8ba3
	s_mul_i32 s1, s0, 1408
	s_sub_u32 s1, s47, s1
	s_mul_hi_u32 s2, s1, 0x2e8ba2f
	s_mul_i32 s8, s2, 88
	s_sub_u32 s8, s1, s8
	s_mul_i32 s9, s0, 0x2c00000
	s_mul_i32 s28, s2, 0x2c0000
	s_add_u32 s9, s9, s28
	s_lshl_b32 s8, s8, 8
	s_add_u32 s9, s9, s8
	s_add_u32 s42, s50, s9
	s_addc_u32 s43, s51, 0
	s_mov_b32 m0, s48
	s_add_u32 s49, s48, 0x400
	global_load_lds_dwordx4 v0, s[42:43]
	s_mov_b32 m0, s49
	s_add_u32 s49, s48, 0x800
	global_load_lds_dwordx4 v1, s[42:43]
	s_mov_b32 m0, s49
	s_add_u32 s49, s48, 0xc00
	global_load_lds_dwordx4 v2, s[42:43]
	s_mov_b32 m0, s49
	s_nop 0
	global_load_lds_dwordx4 v3, s[42:43]
	s_branch .Ldf_dgate_lj

; __device__ __forceinline__ unsigned cvt_pk_bf16(float lo, float hi) { unsigned r; asm volatile("v_cvt_pk_bf16_f32 %0, %1, %2" : "=v"(r) : "v"(lo), "v"(hi)); return r; }
; __device__ __forceinline__ void lds_barrier() { asm volatile("s_waitcnt lgkmcnt(0)" ::: "memory"); __builtin_amdgcn_s_barrier(); asm volatile("" ::: "memory"); }
; #define CVT_LOAD(tile_) do { const int k0_ = ((tile_) / ntn) << 7, n0_ = ((tile_) % ntn) << 6; \
;         _Pragma("unroll") for (int pp = 0; pp < 4; ++pp) pv[pp] = *(const float4*)(src + (size_t)(k0_ + lk + 32 * pp) * N + n0_ + ln4); } while (0)
; __device__ __forceinline__ void convT_job(const float* __restrict__ src, bf16_t* __restrict__ dst, int K, int N, int mode, float* t) {
;     ...
;         const int k0 = (tile / ntn) << 7, n0 = (tile % ntn) << 6;
; #pragma unroll
;         for (int pp = 0; pp < 4; ++pp) { const int k = lk + 32 * pp; t[k * 65 + ln4] = pv[pp].x; t[k * 65 + ln4 + 1] = pv[pp].y; t[k * 65 + ln4 + 2] = pv[pp].z; t[k * 65 + ln4 + 3] = pv[pp].w; }
;         if (tile + (int)gridDim.x < ntiles) CVT_LOAD(tile + (int)gridDim.x);
;         lds_barrier();
;         const int n = tid >> 3, k16 = (tid & 7) * 16;
;         float v[16];
; #pragma unroll
;         for (int j = 0; j < 16; ++j) v[j] = t[(k16 + j) * 65 + n];
;         const int nn = n0 + n;
;         const int row = mode == 0 ? nn : (256 * (nn >> 7) + (nn & 127) + (mode == 2 ? 128 : 0));
;         u32x4 w0, w1; w0.x = cvt_pk_bf16(v[0], v[1]); w0.y = cvt_pk_bf16(v[2], v[3]); w0.z = cvt_pk_bf16(v[4], v[5]); w0.w = cvt_pk_bf16(v[6], v[7]);
;         w1.x = cvt_pk_bf16(v[8], v[9]); w1.y = cvt_pk_bf16(v[10], v[11]); w1.z = cvt_pk_bf16(v[12], v[13]); w1.w = cvt_pk_bf16(v[14], v[15]);
;         bf16_t* d = dst + (size_t)row * K + k0 + k16;
;         *(u32x4*)d = w0; *(u32x4*)(d + 8) = w1;
;         lds_barrier();
; __device__ __forceinline__ void phase_convert(const Params& p, unsigned char* smem) {
;     ...
;     for (int l = 0; l < 2; ++l) {
;         for (int f = 0; f < 2; ++f) {
;             const size_t wo = (size_t)(l * 2 + f) * 2048 * 5632;
;             bf16_t* gu = (bf16_t*)(p.ws + OFF_GU + (size_t)(l * 2 + f) * SZ_GU);
;             convT_job(p.in[3] + wo, gu, 2048, 5632, 1, t);
;             convT_job(p.in[4] + wo, gu, 2048, 5632, 2, t);
.Ldf_dgate_lj:
	v_add_u32_e32 v7, s41, v4
	ds_read2st64_b32 v[8:9], v7 offset0:0 offset1:1
	ds_read2st64_b32 v[10:11], v7 offset0:2 offset1:3
	ds_read2st64_b32 v[12:13], v7 offset0:4 offset1:5
	ds_read2st64_b32 v[14:15], v7 offset0:6 offset1:7
	ds_read2st64_b32 v[16:17], v7 offset0:8 offset1:9
	ds_read2st64_b32 v[18:19], v7 offset0:10 offset1:11
	ds_read2st64_b32 v[20:21], v7 offset0:12 offset1:13
	ds_read2st64_b32 v[22:23], v7 offset0:14 offset1:15
	s_mul_hi_u32 s0, s40, 0x2e8ba3
	s_mul_i32 s1, s0, 1408
	s_sub_u32 s1, s40, s1
	s_mul_hi_u32 s2, s1, 0x2e8ba2f
	s_mul_i32 s8, s2, 88
	s_sub_u32 s8, s1, s8
	s_lshr_b32 s9, s8, 1
	s_lshl_b32 s9, s9, 8
	s_and_b32 s28, s8, 1
	s_lshl_b32 s28, s28, 6
	s_add_u32 s9, s9, s28
	s_mul_i32 s9, s9, 0x1000
	s_mul_i32 s28, s0, 0x2c00000
	s_add_u32 s9, s9, s28
	s_lshl_b32 s2, s2, 8
	s_add_u32 s9, s9, s2
	s_add_u32 s9, s9, s52
	s_add_u32 s44, s54, s9
	s_addc_u32 s45, s55, 0
	s_waitcnt lgkmcnt(6)
	v_cvt_pk_bf16_f32 v8, v8, v9
	v_cvt_pk_bf16_f32 v9, v10, v11
	s_waitcnt lgkmcnt(4)
	v_cvt_pk_bf16_f32 v10, v12, v13
	v_cvt_pk_bf16_f32 v11, v14, v15
	s_waitcnt lgkmcnt(2)
	v_cvt_pk_bf16_f32 v12, v16, v17
	v_cvt_pk_bf16_f32 v13, v18, v19
	s_waitcnt lgkmcnt(0)
	v_cvt_pk_bf16_f32 v14, v20, v21
	v_cvt_pk_bf16_f32 v15, v22, v23
	global_store_dwordx4 v5, v[8:11], s[44:45]
	global_store_dwordx4 v5, v[12:15], s[44:45] offset:16
	s_add_u32 s40, s40, 128
	s_add_u32 s41, s41, 0x8000
	s_and_b32 s41, s41, 0x1ffff
	s_cmp_lt_u32 s40, 1408
	s_cbranch_scc1 .Ldf_dgate_loop
.Ldf_dgate_skip:
	s_sub_u32 s40, s60, 128
	s_cmp_lt_u32 s40, 1408
	s_cbranch_scc0 .Ldf_dup_skip
	s_mul_i32 s0, s53, 2
	s_add_u32 s0, s0, 1
	s_mul_hi_u32 s1, s0, 0x2c00000
	s_mul_i32 s2, s0, 0x2c00000
	s_add_u32 s50, s72, s2
	s_addc_u32 s51, s73, s1
	s_mul_i32 s52, s0, 0x2c00000
	s_add_u32 s52, s52, 0x8000
	v_mov_b32_e32 v29, 0x5800
	v_mov_b32_e32 v28, 0x1000
	v_mad_u32_u24 v0, v30, v29, v31
	v_mad_u32_u24 v5, v26, v28, v27
	v_add_u32_e32 v1, 0x16000, v0
	v_add_u32_e32 v2, 0x2c000, v0
	v_add_u32_e32 v3, 0x42000, v0
	s_barrier
	s_mov_b32 s41, 0
	s_mov_b32 s47, s40
	s_mov_b32 s48, s46
	s_mul_hi_u32 s0, s47, 0x2e8ba3
	s_mul_i32 s1, s0, 1408
	s_sub_u32 s1, s47, s1
	s_mul_hi_u32 s2, s1, 0x2e8ba2f
	s_mul_i32 s8, s2, 88
	s_sub_u32 s8, s1, s8
	s_mul_i32 s9, s0, 0x2c00000
	s_mul_i32 s28, s2, 0x2c0000
	s_add_u32 s9, s9, s28
	s_lshl_b32 s8, s8, 8
	s_add_u32 s9, s9, s8
	s_add_u32 s42, s50, s9
	s_addc_u32 s43, s51, 0
	s_mov_b32 m0, s48
	s_add_u32 s49, s48, 0x400
	global_load_lds_dwordx4 v0, s[42:43]
	s_mov_b32 m0, s49
	s_add_u32 s49, s48, 0x800
	global_load_lds_dwordx4 v1, s[42:43]
	s_mov_b32 m0, s49
	s_add_u32 s49, s48, 0xc00
	global_load_lds_dwordx4 v2, s[42:43]
	s_mov_b32 m0, s49
	s_nop 0
	global_load_lds_dwordx4 v3, s[42:43]
	global_load_dword v24, v173, s[72:73]
	global_load_dword v24, v173, s[72:73]
	s_add_u32 s47, s40, 128
	s_add_u32 s48, s46, 0x8000
	s_cmp_lt_u32 s47, 1408
	s_cbranch_scc0 .Ldf_dup_pd1
	s_mul_hi_u32 s0, s47, 0x2e8ba3
	s_mul_i32 s1, s0, 1408
	s_sub_u32 s1, s47, s1
	s_mul_hi_u32 s2, s1, 0x2e8ba2f
	s_mul_i32 s8, s2, 88
	s_sub_u32 s8, s1, s8
	s_mul_i32 s9, s0, 0x2c00000
	s_mul_i32 s28, s2, 0x2c0000
	s_add_u32 s9, s9, s28
	s_lshl_b32 s8, s8, 8
	s_add_u32 s9, s9, s8
	s_add_u32 s42, s50, s9
	s_addc_u32 s43, s51, 0
	s_mov_b32 m0, s48
	s_add_u32 s49, s48, 0x400
	global_load_lds_dwordx4 v0, s[42:43]
	s_mov_b32 m0, s49
	s_add_u32 s49, s48, 0x800
	global_load_lds_dwordx4 v1, s[42:43]
	s_mov_b32 m0, s49
	s_add_u32 s49, s48, 0xc00
	global_load_lds_dwordx4 v2, s[42:43]
	s_mov_b32 m0, s49
	s_nop 0
	global_load_lds_dwordx4 v3, s[42:43]
	s_branch .Ldf_dup_pj1

; #define CVT_LOAD(tile_) do { const int k0_ = ((tile_) / ntn) << 7, n0_ = ((tile_) % ntn) << 6; \
;         _Pragma("unroll") for (int pp = 0; pp < 4; ++pp) pv[pp] = *(const float4*)(src + (size_t)(k0_ + lk + 32 * pp) * N + n0_ + ln4); } while (0)
; __device__ __forceinline__ void convT_job(const float* __restrict__ src, bf16_t* __restrict__ dst, int K, int N, int mode, float* t) {
;     ...
;     int tile = blockIdx.x;
;     if (tile < ntiles) CVT_LOAD(tile);
;     ...
;         if (tile + (int)gridDim.x < ntiles) CVT_LOAD(tile + (int)gridDim.x);
.Ldf_dup_pj1:
	global_load_dword v24, v173, s[72:73]
	global_load_dword v24, v173, s[72:73]
	s_add_u32 s47, s40, 256
	s_add_u32 s48, s46, 0x10000
	s_cmp_lt_u32 s47, 1408
	s_cbranch_scc0 .Ldf_dup_pd2
	s_mul_hi_u32 s0, s47, 0x2e8ba3
	s_mul_i32 s1, s0, 1408
	s_sub_u32 s1, s47, s1
	s_mul_hi_u32 s2, s1, 0x2e8ba2f
	s_mul_i32 s8, s2, 88
	s_sub_u32 s8, s1, s8
	s_mul_i32 s9, s0, 0x2c00000
	s_mul_i32 s28, s2, 0x2c0000
	s_add_u32 s9, s9, s28
	s_lshl_b32 s8, s8, 8
	s_add_u32 s9, s9, s8
	s_add_u32 s42, s50, s9
	s_addc_u32 s43, s51, 0
	s_mov_b32 m0, s48
	s_add_u32 s49, s48, 0x400
	global_load_lds_dwordx4 v0, s[42:43]
	s_mov_b32 m0, s49
	s_add_u32 s49, s48, 0x800
	global_load_lds_dwordx4 v1, s[42:43]
	s_mov_b32 m0, s49
	s_add_u32 s49, s48, 0xc00
	global_load_lds_dwordx4 v2, s[42:43]
	s_mov_b32 m0, s49
	s_nop 0
	global_load_lds_dwordx4 v3, s[42:43]
	s_branch .Ldf_dup_pj2

; __device__ __forceinline__ unsigned cvt_pk_bf16(float lo, float hi) { unsigned r; asm volatile("v_cvt_pk_bf16_f32 %0, %1, %2" : "=v"(r) : "v"(lo), "v"(hi)); return r; }
; __device__ __forceinline__ void lds_barrier() { asm volatile("s_waitcnt lgkmcnt(0)" ::: "memory"); __builtin_amdgcn_s_barrier(); asm volatile("" ::: "memory"); }
; #define CVT_LOAD(tile_) do { const int k0_ = ((tile_) / ntn) << 7, n0_ = ((tile_) % ntn) << 6; \
;         _Pragma("unroll") for (int pp = 0; pp < 4; ++pp) pv[pp] = *(const float4*)(src + (size_t)(k0_ + lk + 32 * pp) * N + n0_ + ln4); } while (0)
; __device__ __forceinline__ void convT_job(const float* __restrict__ src, bf16_t* __restrict__ dst, int K, int N, int mode, float* t) {
;     ...
;         const int k0 = (tile / ntn) << 7, n0 = (tile % ntn) << 6;
; #pragma unroll
;         for (int pp = 0; pp < 4; ++pp) { const int k = lk + 32 * pp; t[k * 65 + ln4] = pv[pp].x; t[k * 65 + ln4 + 1] = pv[pp].y; t[k * 65 + ln4 + 2] = pv[pp].z; t[k * 65 + ln4 + 3] = pv[pp].w; }
;         if (tile + (int)gridDim.x < ntiles) CVT_LOAD(tile + (int)gridDim.x);
;         lds_barrier();
;         const int n = tid >> 3, k16 = (tid & 7) * 16;
;         float v[16];
; #pragma unroll
;         for (int j = 0; j < 16; ++j) v[j] = t[(k16 + j) * 65 + n];
;         const int nn = n0 + n;
;         const int row = mode == 0 ? nn : (256 * (nn >> 7) + (nn & 127) + (mode == 2 ? 128 : 0));
;         u32x4 w0, w1; w0.x = cvt_pk_bf16(v[0], v[1]); w0.y = cvt_pk_bf16(v[2], v[3]); w0.z = cvt_pk_bf16(v[4], v[5]); w0.w = cvt_pk_bf16(v[6], v[7]);
;         w1.x = cvt_pk_bf16(v[8], v[9]); w1.y = cvt_pk_bf16(v[10], v[11]); w1.z = cvt_pk_bf16(v[12], v[13]); w1.w = cvt_pk_bf16(v[14], v[15]);
;         bf16_t* d = dst + (size_t)row * K + k0 + k16;
;         *(u32x4*)d = w0; *(u32x4*)(d + 8) = w1;
;         lds_barrier();
; __device__ __forceinline__ void phase_convert(const Params& p, unsigned char* smem) {
;     ...
;             convT_job(p.in[5] + wo, (bf16_t*)(p.ws + OFF_DN + (size_t)(l * 2 + f) * SZ_DN), 5632, 2048, 0, t);
.Ldf_dup_lj:
	v_add_u32_e32 v7, s41, v4
	ds_read2st64_b32 v[8:9], v7 offset0:0 offset1:1
	ds_read2st64_b32 v[10:11], v7 offset0:2 offset1:3
	ds_read2st64_b32 v[12:13], v7 offset0:4 offset1:5
	ds_read2st64_b32 v[14:15], v7 offset0:6 offset1:7
	ds_read2st64_b32 v[16:17], v7 offset0:8 offset1:9
	ds_read2st64_b32 v[18:19], v7 offset0:10 offset1:11
	ds_read2st64_b32 v[20:21], v7 offset0:12 offset1:13
	ds_read2st64_b32 v[22:23], v7 offset0:14 offset1:15
	s_mul_hi_u32 s0, s40, 0x2e8ba3
	s_mul_i32 s1, s0, 1408
	s_sub_u32 s1, s40, s1
	s_mul_hi_u32 s2, s1, 0x2e8ba2f
	s_mul_i32 s8, s2, 88
	s_sub_u32 s8, s1, s8
	s_lshr_b32 s9, s8, 1
	s_lshl_b32 s9, s9, 8
	s_and_b32 s28, s8, 1
	s_lshl_b32 s28, s28, 6
	s_add_u32 s9, s9, s28
	s_add_u32 s9, s9, 128
	s_mul_i32 s9, s9, 0x1000
	s_mul_i32 s28, s0, 0x2c00000
	s_add_u32 s9, s9, s28
	s_lshl_b32 s2, s2, 8
	s_add_u32 s9, s9, s2
	s_add_u32 s9, s9, s52
	s_add_u32 s44, s54, s9
	s_addc_u32 s45, s55, 0
	s_waitcnt lgkmcnt(6)
	v_cvt_pk_bf16_f32 v8, v8, v9
	v_cvt_pk_bf16_f32 v9, v10, v11
	s_waitcnt lgkmcnt(4)
	v_cvt_pk_bf16_f32 v10, v12, v13
	v_cvt_pk_bf16_f32 v11, v14, v15
	s_waitcnt lgkmcnt(2)
	v_cvt_pk_bf16_f32 v12, v16, v17
	v_cvt_pk_bf16_f32 v13, v18, v19
	s_waitcnt lgkmcnt(0)
	v_cvt_pk_bf16_f32 v14, v20, v21
	v_cvt_pk_bf16_f32 v15, v22, v23
	global_store_dwordx4 v5, v[8:11], s[44:45]
	global_store_dwordx4 v5, v[12:15], s[44:45] offset:16
	s_add_u32 s40, s40, 128
	s_add_u32 s41, s41, 0x8000
	s_and_b32 s41, s41, 0x1ffff
	s_cmp_lt_u32 s40, 1408
	s_cbranch_scc1 .Ldf_dup_loop
.Ldf_dup_skip:
	s_sub_u32 s40, s60, 128
	s_cmp_lt_u32 s40, 1408
	s_cbranch_scc0 .Ldf_ddown_skip
	s_mul_i32 s0, s53, 2
	s_add_u32 s0, s0, 1
	s_mul_hi_u32 s1, s0, 0x2c00000
	s_mul_i32 s2, s0, 0x2c00000
	s_add_u32 s50, s74, s2
	s_addc_u32 s51, s75, s1
	s_mul_i32 s52, s0, 0x1600000
	s_add_u32 s52, s52, 0xb008000
	v_mov_b32_e32 v29, 0x2000
	v_mov_b32_e32 v28, 0x2c00
	v_mad_u32_u24 v0, v30, v29, v31
	v_mad_u32_u24 v5, v26, v28, v27
	v_add_u32_e32 v1, 0x8000, v0
	v_add_u32_e32 v2, 0x10000, v0
	v_add_u32_e32 v3, 0x18000, v0
	s_barrier
	s_mov_b32 s41, 0
	s_mov_b32 s47, s40
	s_mov_b32 s48, s46
	s_mul_hi_u32 s0, s47, 0x2e8ba3
	s_mul_i32 s1, s0, 1408
	s_sub_u32 s1, s47, s1
	s_mul_hi_u32 s2, s1, 0x8000001
	s_mul_i32 s8, s2, 32
	s_sub_u32 s8, s1, s8
	s_mul_i32 s9, s0, 0x2c00000
	s_mul_i32 s28, s2, 0x100000
	s_add_u32 s9, s9, s28
	s_lshl_b32 s8, s8, 8
	s_add_u32 s9, s9, s8
	s_add_u32 s42, s50, s9
	s_addc_u32 s43, s51, 0
	s_mov_b32 m0, s48
	s_add_u32 s49, s48, 0x400
	global_load_lds_dwordx4 v0, s[42:43]
	s_mov_b32 m0, s49
	s_add_u32 s49, s48, 0x800
	global_load_lds_dwordx4 v1, s[42:43]
	s_mov_b32 m0, s49
	s_add_u32 s49, s48, 0xc00
	global_load_lds_dwordx4 v2, s[42:43]
	s_mov_b32 m0, s49
	s_nop 0
	global_load_lds_dwordx4 v3, s[42:43]
	global_load_dword v24, v173, s[74:75]
	global_load_dword v24, v173, s[74:75]
	s_add_u32 s47, s40, 128
	s_add_u32 s48, s46, 0x8000
	s_cmp_lt_u32 s47, 1408
	s_cbranch_scc0 .Ldf_ddown_pd1
	s_mul_hi_u32 s0, s47, 0x2e8ba3
	s_mul_i32 s1, s0, 1408
	s_sub_u32 s1, s47, s1
	s_mul_hi_u32 s2, s1, 0x8000001
	s_mul_i32 s8, s2, 32
	s_sub_u32 s8, s1, s8
	s_mul_i32 s9, s0, 0x2c00000
	s_mul_i32 s28, s2, 0x100000
	s_add_u32 s9, s9, s28
	s_lshl_b32 s8, s8, 8
	s_add_u32 s9, s9, s8
	s_add_u32 s42, s50, s9
	s_addc_u32 s43, s51, 0
	s_mov_b32 m0, s48
	s_add_u32 s49, s48, 0x400
	global_load_lds_dwordx4 v0, s[42:43]
	s_mov_b32 m0, s49
	s_add_u32 s49, s48, 0x800
	global_load_lds_dwordx4 v1, s[42:43]
	s_mov_b32 m0, s49
	s_add_u32 s49, s48, 0xc00
	global_load_lds_dwordx4 v2, s[42:43]
	s_mov_b32 m0, s49
	s_nop 0
	global_load_lds_dwordx4 v3, s[42:43]
	s_branch .Ldf_ddown_pj1

; #define CVT_LOAD(tile_) do { const int k0_ = ((tile_) / ntn) << 7, n0_ = ((tile_) % ntn) << 6; \
;         _Pragma("unroll") for (int pp = 0; pp < 4; ++pp) pv[pp] = *(const float4*)(src + (size_t)(k0_ + lk + 32 * pp) * N + n0_ + ln4); } while (0)
; __device__ __forceinline__ void convT_job(const float* __restrict__ src, bf16_t* __restrict__ dst, int K, int N, int mode, float* t) {
;     ...
;     int tile = blockIdx.x;
;     if (tile < ntiles) CVT_LOAD(tile);
.Ldf_ddown_pj1:
	global_load_dword v24, v173, s[74:75]
	global_load_dword v24, v173, s[74:75]
	s_add_u32 s47, s40, 256
	s_add_u32 s48, s46, 0x10000
	s_cmp_lt_u32 s47, 1408
	s_cbranch_scc0 .Ldf_ddown_pd2
	s_mul_hi_u32 s0, s47, 0x2e8ba3
	s_mul_i32 s1, s0, 1408
	s_sub_u32 s1, s47, s1
	s_mul_hi_u32 s2, s1, 0x8000001
	s_mul_i32 s8, s2, 32
	s_sub_u32 s8, s1, s8
	s_mul_i32 s9, s0, 0x2c00000
	s_mul_i32 s28, s2, 0x100000
	s_add_u32 s9, s9, s28
	s_lshl_b32 s8, s8, 8
	s_add_u32 s9, s9, s8
	s_add_u32 s42, s50, s9
	s_addc_u32 s43, s51, 0
	s_mov_b32 m0, s48
	s_add_u32 s49, s48, 0x400
	global_load_lds_dwordx4 v0, s[42:43]
	s_mov_b32 m0, s49
	s_add_u32 s49, s48, 0x800
	global_load_lds_dwordx4 v1, s[42:43]
	s_mov_b32 m0, s49
	s_add_u32 s49, s48, 0xc00
	global_load_lds_dwordx4 v2, s[42:43]
	s_mov_b32 m0, s49
	s_nop 0
	global_load_lds_dwordx4 v3, s[42:43]
	s_branch .Ldf_ddown_pj2

; __device__ __forceinline__ void lds_barrier() { asm volatile("s_waitcnt lgkmcnt(0)" ::: "memory"); __builtin_amdgcn_s_barrier(); asm volatile("" ::: "memory"); }
; #define CVT_LOAD(tile_) do { const int k0_ = ((tile_) / ntn) << 7, n0_ = ((tile_) % ntn) << 6; \
;         _Pragma("unroll") for (int pp = 0; pp < 4; ++pp) pv[pp] = *(const float4*)(src + (size_t)(k0_ + lk + 32 * pp) * N + n0_ + ln4); } while (0)
; __device__ __forceinline__ void convT_job(const float* __restrict__ src, bf16_t* __restrict__ dst, int K, int N, int mode, float* t) {
;     ...
;     for (; tile < ntiles; tile += gridDim.x) {
;         const int k0 = (tile / ntn) << 7, n0 = (tile % ntn) << 6;
; #pragma unroll
;         for (int pp = 0; pp < 4; ++pp) { const int k = lk + 32 * pp; t[k * 65 + ln4] = pv[pp].x; t[k * 65 + ln4 + 1] = pv[pp].y; t[k * 65 + ln4 + 2] = pv[pp].z; t[k * 65 + ln4 + 3] = pv[pp].w; }
;         if (tile + (int)gridDim.x < ntiles) CVT_LOAD(tile + (int)gridDim.x);
;         lds_barrier();
.Ldf_ddown_loop:
	s_waitcnt vmcnt(14)
	s_barrier
	s_add_u32 s47, s40, 384
	s_add_u32 s48, s41, 0x18000
	s_and_b32 s48, s48, 0x1ffff
	s_add_u32 s48, s48, s46
	s_cmp_lt_u32 s47, 1408
	s_cbranch_scc0 .Ldf_ddown_ld
	s_mul_hi_u32 s0, s47, 0x2e8ba3
	s_mul_i32 s1, s0, 1408
	s_sub_u32 s1, s47, s1
	s_mul_hi_u32 s2, s1, 0x8000001
	s_mul_i32 s8, s2, 32
	s_sub_u32 s8, s1, s8
	s_mul_i32 s9, s0, 0x2c00000
	s_mul_i32 s28, s2, 0x100000
	s_add_u32 s9, s9, s28
	s_lshl_b32 s8, s8, 8
	s_add_u32 s9, s9, s8
	s_add_u32 s42, s50, s9
	s_addc_u32 s43, s51, 0
	s_mov_b32 m0, s48
	s_add_u32 s49, s48, 0x400
	global_load_lds_dwordx4 v0, s[42:43]
	s_mov_b32 m0, s49
	s_add_u32 s49, s48, 0x800
	global_load_lds_dwordx4 v1, s[42:43]
	s_mov_b32 m0, s49
	s_add_u32 s49, s48, 0xc00
	global_load_lds_dwordx4 v2, s[42:43]
	s_mov_b32 m0, s49
	s_nop 0
	global_load_lds_dwordx4 v3, s[42:43]
	s_branch .Ldf_ddown_lj

; __device__ __forceinline__ unsigned cvt_pk_bf16(float lo, float hi) { unsigned r; asm volatile("v_cvt_pk_bf16_f32 %0, %1, %2" : "=v"(r) : "v"(lo), "v"(hi)); return r; }
; __device__ __forceinline__ void lds_barrier() { asm volatile("s_waitcnt lgkmcnt(0)" ::: "memory"); __builtin_amdgcn_s_barrier(); asm volatile("" ::: "memory"); }
; __device__ __forceinline__ void convT_job(const float* __restrict__ src, bf16_t* __restrict__ dst, int K, int N, int mode, float* t) {
;     ...
;         const int k0 = (tile / ntn) << 7, n0 = (tile % ntn) << 6;
; #pragma unroll
;         for (int pp = 0; pp < 4; ++pp) { const int k = lk + 32 * pp; t[k * 65 + ln4] = pv[pp].x; t[k * 65 + ln4 + 1] = pv[pp].y; t[k * 65 + ln4 + 2] = pv[pp].z; t[k * 65 + ln4 + 3] = pv[pp].w; }
;         if (tile + (int)gridDim.x < ntiles) CVT_LOAD(tile + (int)gridDim.x);
;         lds_barrier();
;         const int n = tid >> 3, k16 = (tid & 7) * 16;
;         float v[16];
; #pragma unroll
;         for (int j = 0; j < 16; ++j) v[j] = t[(k16 + j) * 65 + n];
;         const int nn = n0 + n;
;         const int row = mode == 0 ? nn : (256 * (nn >> 7) + (nn & 127) + (mode == 2 ? 128 : 0));
;         u32x4 w0, w1; w0.x = cvt_pk_bf16(v[0], v[1]); w0.y = cvt_pk_bf16(v[2], v[3]); w0.z = cvt_pk_bf16(v[4], v[5]); w0.w = cvt_pk_bf16(v[6], v[7]);
;         w1.x = cvt_pk_bf16(v[8], v[9]); w1.y = cvt_pk_bf16(v[10], v[11]); w1.z = cvt_pk_bf16(v[12], v[13]); w1.w = cvt_pk_bf16(v[14], v[15]);
;         bf16_t* d = dst + (size_t)row * K + k0 + k16;
;         *(u32x4*)d = w0; *(u32x4*)(d + 8) = w1;
;         lds_barrier();
; __device__ __forceinline__ void phase_convert(const Params& p, unsigned char* smem) {
;     ...
;     for (int l = 0; l < 2; ++l) {
;         for (int f = 0; f < 2; ++f) {
;             const size_t wo = (size_t)(l * 2 + f) * 2048 * 5632;
;             bf16_t* gu = (bf16_t*)(p.ws + OFF_GU + (size_t)(l * 2 + f) * SZ_GU);
;             convT_job(p.in[3] + wo, gu, 2048, 5632, 1, t);
;             convT_job(p.in[4] + wo, gu, 2048, 5632, 2, t);
;             convT_job(p.in[5] + wo, (bf16_t*)(p.ws + OFF_DN + (size_t)(l * 2 + f) * SZ_DN), 5632, 2048, 0, t);
;         }
;         convT_job(p.in[6] + (size_t)l * 2048 * 5632, (bf16_t*)(p.ws + OFF_IN + (size_t)l * SZ_IN), 2048, 5632, 0, t);
;         convT_job(p.in[7] + (size_t)l * 2048 * 2048, (bf16_t*)(p.ws + OFF_OUT + (size_t)l * SZ_OUT), 2048, 2048, 0, t);
.Ldf_ddown_lj:
	v_add_u32_e32 v7, s41, v4
	ds_read2st64_b32 v[8:9], v7 offset0:0 offset1:1
	ds_read2st64_b32 v[10:11], v7 offset0:2 offset1:3
	ds_read2st64_b32 v[12:13], v7 offset0:4 offset1:5
	ds_read2st64_b32 v[14:15], v7 offset0:6 offset1:7
	ds_read2st64_b32 v[16:17], v7 offset0:8 offset1:9
	ds_read2st64_b32 v[18:19], v7 offset0:10 offset1:11
	ds_read2st64_b32 v[20:21], v7 offset0:12 offset1:13
	ds_read2st64_b32 v[22:23], v7 offset0:14 offset1:15
	s_mul_hi_u32 s0, s40, 0x2e8ba3
	s_mul_i32 s1, s0, 1408
	s_sub_u32 s1, s40, s1
	s_mul_hi_u32 s2, s1, 0x8000001
	s_mul_i32 s8, s2, 32
	s_sub_u32 s8, s1, s8
	s_lshl_b32 s9, s8, 6
	s_mul_i32 s9, s9, 0x2c00
	s_mul_i32 s28, s0, 0x1600000
	s_add_u32 s9, s9, s28
	s_lshl_b32 s2, s2, 8
	s_add_u32 s9, s9, s2
	s_add_u32 s9, s9, s52
	s_add_u32 s44, s54, s9
	s_addc_u32 s45, s55, 0
	s_waitcnt lgkmcnt(6)
	v_cvt_pk_bf16_f32 v8, v8, v9
	v_cvt_pk_bf16_f32 v9, v10, v11
	s_waitcnt lgkmcnt(4)
	v_cvt_pk_bf16_f32 v10, v12, v13
	v_cvt_pk_bf16_f32 v11, v14, v15
	s_waitcnt lgkmcnt(2)
	v_cvt_pk_bf16_f32 v12, v16, v17
	v_cvt_pk_bf16_f32 v13, v18, v19
	s_waitcnt lgkmcnt(0)
	v_cvt_pk_bf16_f32 v14, v20, v21
	v_cvt_pk_bf16_f32 v15, v22, v23
	global_store_dwordx4 v5, v[8:11], s[44:45]
	global_store_dwordx4 v5, v[12:15], s[44:45] offset:16
	s_add_u32 s40, s40, 128
	s_add_u32 s41, s41, 0x8000
	s_and_b32 s41, s41, 0x1ffff
	s_cmp_lt_u32 s40, 1408
	s_cbranch_scc1 .Ldf_ddown_loop
.Ldf_ddown_skip:
	s_sub_u32 s40, s60, 128
	s_cmp_lt_u32 s40, 512
	s_cbranch_scc0 .Ldf_dwout_skip
	s_mul_i32 s0, s53, 1
	s_mul_hi_u32 s1, s0, 0x1000000
	s_mul_i32 s2, s0, 0x1000000
	s_add_u32 s50, s78, s2
	s_addc_u32 s51, s79, s1
	s_mul_i32 s52, s0, 0x800000
	s_add_u32 s52, s52, 0x13408000
	v_mov_b32_e32 v29, 0x2000
	v_mov_b32_e32 v28, 0x1000
	v_mad_u32_u24 v0, v30, v29, v31
	v_mad_u32_u24 v5, v26, v28, v27
	v_add_u32_e32 v1, 0x8000, v0
	v_add_u32_e32 v2, 0x10000, v0
	v_add_u32_e32 v3, 0x18000, v0
	s_barrier
	s_mov_b32 s41, 0
	s_mov_b32 s47, s40
	s_mov_b32 s48, s46
	s_mul_hi_u32 s0, s47, 0x800001
	s_mul_i32 s1, s0, 512
	s_sub_u32 s1, s47, s1
	s_mul_hi_u32 s2, s1, 0x8000001
	s_mul_i32 s8, s2, 32
	s_sub_u32 s8, s1, s8
	s_mul_i32 s9, s0, 0x1000000
	s_mul_i32 s28, s2, 0x100000
	s_add_u32 s9, s9, s28
	s_lshl_b32 s8, s8, 8
	s_add_u32 s9, s9, s8
	s_add_u32 s42, s50, s9
	s_addc_u32 s43, s51, 0
	s_mov_b32 m0, s48
	s_add_u32 s49, s48, 0x400
	global_load_lds_dwordx4 v0, s[42:43]
	s_mov_b32 m0, s49
	s_add_u32 s49, s48, 0x800
	global_load_lds_dwordx4 v1, s[42:43]
	s_mov_b32 m0, s49
	s_add_u32 s49, s48, 0xc00
	global_load_lds_dwordx4 v2, s[42:43]
	s_mov_b32 m0, s49
	s_nop 0
	global_load_lds_dwordx4 v3, s[42:43]
	global_load_dword v24, v173, s[78:79]
	global_load_dword v24, v173, s[78:79]
	s_add_u32 s47, s40, 128
	s_add_u32 s48, s46, 0x8000
	s_cmp_lt_u32 s47, 512
	s_cbranch_scc0 .Ldf_dwout_pd1
	s_mul_hi_u32 s0, s47, 0x800001
	s_mul_i32 s1, s0, 512
	s_sub_u32 s1, s47, s1
	s_mul_hi_u32 s2, s1, 0x8000001
	s_mul_i32 s8, s2, 32
	s_sub_u32 s8, s1, s8
	s_mul_i32 s9, s0, 0x1000000
	s_mul_i32 s28, s2, 0x100000
	s_add_u32 s9, s9, s28
	s_lshl_b32 s8, s8, 8
	s_add_u32 s9, s9, s8
	s_add_u32 s42, s50, s9
	s_addc_u32 s43, s51, 0
	s_mov_b32 m0, s48
	s_add_u32 s49, s48, 0x400
	global_load_lds_dwordx4 v0, s[42:43]
	s_mov_b32 m0, s49
	s_add_u32 s49, s48, 0x800
	global_load_lds_dwordx4 v1, s[42:43]
	s_mov_b32 m0, s49
	s_add_u32 s49, s48, 0xc00
	global_load_lds_dwordx4 v2, s[42:43]
	s_mov_b32 m0, s49
	s_nop 0
	global_load_lds_dwordx4 v3, s[42:43]
	s_branch .Ldf_dwout_pj1

; #define CVT_LOAD(tile_) do { const int k0_ = ((tile_) / ntn) << 7, n0_ = ((tile_) % ntn) << 6; \
;         _Pragma("unroll") for (int pp = 0; pp < 4; ++pp) pv[pp] = *(const float4*)(src + (size_t)(k0_ + lk + 32 * pp) * N + n0_ + ln4); } while (0)
; __device__ __forceinline__ void convT_job(const float* __restrict__ src, bf16_t* __restrict__ dst, int K, int N, int mode, float* t) {
;     ...
;     int tile = blockIdx.x;
;     if (tile < ntiles) CVT_LOAD(tile);
.Ldf_dwout_pj1:
	global_load_dword v24, v173, s[78:79]
	global_load_dword v24, v173, s[78:79]
	s_add_u32 s47, s40, 256
	s_add_u32 s48, s46, 0x10000
	s_cmp_lt_u32 s47, 512
	s_cbranch_scc0 .Ldf_dwout_pd2
	s_mul_hi_u32 s0, s47, 0x800001
	s_mul_i32 s1, s0, 512
	s_sub_u32 s1, s47, s1
	s_mul_hi_u32 s2, s1, 0x8000001
	s_mul_i32 s8, s2, 32
	s_sub_u32 s8, s1, s8
	s_mul_i32 s9, s0, 0x1000000
	s_mul_i32 s28, s2, 0x100000
	s_add_u32 s9, s9, s28
	s_lshl_b32 s8, s8, 8
	s_add_u32 s9, s9, s8
	s_add_u32 s42, s50, s9
	s_addc_u32 s43, s51, 0
	s_mov_b32 m0, s48
	s_add_u32 s49, s48, 0x400
	global_load_lds_dwordx4 v0, s[42:43]
	s_mov_b32 m0, s49
	s_add_u32 s49, s48, 0x800
	global_load_lds_dwordx4 v1, s[42:43]
	s_mov_b32 m0, s49
	s_add_u32 s49, s48, 0xc00
	global_load_lds_dwordx4 v2, s[42:43]
	s_mov_b32 m0, s49
	s_nop 0
	global_load_lds_dwordx4 v3, s[42:43]
	s_branch .Ldf_dwout_pj2

; __device__ __forceinline__ void lds_barrier() { asm volatile("s_waitcnt lgkmcnt(0)" ::: "memory"); __builtin_amdgcn_s_barrier(); asm volatile("" ::: "memory"); }
; #define CVT_LOAD(tile_) do { const int k0_ = ((tile_) / ntn) << 7, n0_ = ((tile_) % ntn) << 6; \
;         _Pragma("unroll") for (int pp = 0; pp < 4; ++pp) pv[pp] = *(const float4*)(src + (size_t)(k0_ + lk + 32 * pp) * N + n0_ + ln4); } while (0)
; __device__ __forceinline__ void convT_job(const float* __restrict__ src, bf16_t* __restrict__ dst, int K, int N, int mode, float* t) {
;     ...
;     for (; tile < ntiles; tile += gridDim.x) {
;         const int k0 = (tile / ntn) << 7, n0 = (tile % ntn) << 6;
; #pragma unroll
;         for (int pp = 0; pp < 4; ++pp) { const int k = lk + 32 * pp; t[k * 65 + ln4] = pv[pp].x; t[k * 65 + ln4 + 1] = pv[pp].y; t[k * 65 + ln4 + 2] = pv[pp].z; t[k * 65 + ln4 + 3] = pv[pp].w; }
;         if (tile + (int)gridDim.x < ntiles) CVT_LOAD(tile + (int)gridDim.x);
;         lds_barrier();
.Ldf_dwout_loop:
	s_waitcnt vmcnt(14)
	s_barrier
	s_add_u32 s47, s40, 384
	s_add_u32 s48, s41, 0x18000
	s_and_b32 s48, s48, 0x1ffff
	s_add_u32 s48, s48, s46
	s_cmp_lt_u32 s47, 512
	s_cbranch_scc0 .Ldf_dwout_ld
	s_mul_hi_u32 s0, s47, 0x800001
	s_mul_i32 s1, s0, 512
	s_sub_u32 s1, s47, s1
	s_mul_hi_u32 s2, s1, 0x8000001
	s_mul_i32 s8, s2, 32
	s_sub_u32 s8, s1, s8
	s_mul_i32 s9, s0, 0x1000000
	s_mul_i32 s28, s2, 0x100000
	s_add_u32 s9, s9, s28
	s_lshl_b32 s8, s8, 8
	s_add_u32 s9, s9, s8
	s_add_u32 s42, s50, s9
	s_addc_u32 s43, s51, 0
	s_mov_b32 m0, s48
	s_add_u32 s49, s48, 0x400
	global_load_lds_dwordx4 v0, s[42:43]
	s_mov_b32 m0, s49
	s_add_u32 s49, s48, 0x800
	global_load_lds_dwordx4 v1, s[42:43]
	s_mov_b32 m0, s49
	s_add_u32 s49, s48, 0xc00
	global_load_lds_dwordx4 v2, s[42:43]
	s_mov_b32 m0, s49
	s_nop 0
	global_load_lds_dwordx4 v3, s[42:43]
	s_branch .Ldf_dwout_lj

; __device__ __forceinline__ unsigned cvt_pk_bf16(float lo, float hi) { unsigned r; asm volatile("v_cvt_pk_bf16_f32 %0, %1, %2" : "=v"(r) : "v"(lo), "v"(hi)); return r; }
; __device__ __forceinline__ void lds_barrier() { asm volatile("s_waitcnt lgkmcnt(0)" ::: "memory"); __builtin_amdgcn_s_barrier(); asm volatile("" ::: "memory"); }
; __device__ __forceinline__ void convT_job(const float* __restrict__ src, bf16_t* __restrict__ dst, int K, int N, int mode, float* t) {
;     ...
;         const int n = tid >> 3, k16 = (tid & 7) * 16;
;         float v[16];
; #pragma unroll
;         for (int j = 0; j < 16; ++j) v[j] = t[(k16 + j) * 65 + n];
;         const int nn = n0 + n;
;         const int row = mode == 0 ? nn : (256 * (nn >> 7) + (nn & 127) + (mode == 2 ? 128 : 0));
;         u32x4 w0, w1; w0.x = cvt_pk_bf16(v[0], v[1]); w0.y = cvt_pk_bf16(v[2], v[3]); w0.z = cvt_pk_bf16(v[4], v[5]); w0.w = cvt_pk_bf16(v[6], v[7]);
;         w1.x = cvt_pk_bf16(v[8], v[9]); w1.y = cvt_pk_bf16(v[10], v[11]); w1.z = cvt_pk_bf16(v[12], v[13]); w1.w = cvt_pk_bf16(v[14], v[15]);
;         bf16_t* d = dst + (size_t)row * K + k0 + k16;
;         *(u32x4*)d = w0; *(u32x4*)(d + 8) = w1;
;         lds_barrier();
.Ldf_dwout_lj:
	v_add_u32_e32 v7, s41, v4
	ds_read2st64_b32 v[8:9], v7 offset0:0 offset1:1
	ds_read2st64_b32 v[10:11], v7 offset0:2 offset1:3
	ds_read2st64_b32 v[12:13], v7 offset0:4 offset1:5
	ds_read2st64_b32 v[14:15], v7 offset0:6 offset1:7
	ds_read2st64_b32 v[16:17], v7 offset0:8 offset1:9
	ds_read2st64_b32 v[18:19], v7 offset0:10 offset1:11
	ds_read2st64_b32 v[20:21], v7 offset0:12 offset1:13
	ds_read2st64_b32 v[22:23], v7 offset0:14 offset1:15
	s_mul_hi_u32 s0, s40, 0x800001
	s_mul_i32 s1, s0, 512
	s_sub_u32 s1, s40, s1
	s_mul_hi_u32 s2, s1, 0x8000001
	s_mul_i32 s8, s2, 32
	s_sub_u32 s8, s1, s8
	s_lshl_b32 s9, s8, 6
	s_mul_i32 s9, s9, 0x1000
	s_mul_i32 s28, s0, 0x800000
	s_add_u32 s9, s9, s28
	s_lshl_b32 s2, s2, 8
	s_add_u32 s9, s9, s2
	s_add_u32 s9, s9, s52
	s_add_u32 s44, s54, s9
	s_addc_u32 s45, s55, 0
	s_waitcnt lgkmcnt(6)
	v_cvt_pk_bf16_f32 v8, v8, v9
	v_cvt_pk_bf16_f32 v9, v10, v11
	s_waitcnt lgkmcnt(4)
	v_cvt_pk_bf16_f32 v10, v12, v13
	v_cvt_pk_bf16_f32 v11, v14, v15
	s_waitcnt lgkmcnt(2)
	v_cvt_pk_bf16_f32 v12, v16, v17
	v_cvt_pk_bf16_f32 v13, v18, v19
	s_waitcnt lgkmcnt(0)
	v_cvt_pk_bf16_f32 v14, v20, v21
	v_cvt_pk_bf16_f32 v15, v22, v23
	global_store_dwordx4 v5, v[8:11], s[44:45]
	global_store_dwordx4 v5, v[12:15], s[44:45] offset:16
	s_add_u32 s40, s40, 128
	s_add_u32 s41, s41, 0x8000
	s_and_b32 s41, s41, 0x1ffff
	s_cmp_lt_u32 s40, 512
	s_cbranch_scc1 .Ldf_dwout_loop

; __device__ __forceinline__ void run_phase(const Params& p, int ph, unsigned char* smem, int rep) {
;     ...
;     } else if (k == 3) {
;         gemm_in(XB, (const bf16_t*)(p.ws + OFF_IN + (size_t)l * SZ_IN), H);
.Ldf_end:
.LBB0_544:
	s_mov_b64 s[0:1], 0

; __device__ __forceinline__ int opaque_tid() { int t = threadIdx.x; asm volatile("" : "+v"(t)); return t; }
; #define CVT_LOAD(tile_) do { const int k0_ = ((tile_) / ntn) << 7, n0_ = ((tile_) % ntn) << 6; \
;         _Pragma("unroll") for (int pp = 0; pp < 4; ++pp) pv[pp] = *(const float4*)(src + (size_t)(k0_ + lk + 32 * pp) * N + n0_ + ln4); } while (0)
; __device__ __forceinline__ void convT_job(const float* __restrict__ src, bf16_t* __restrict__ dst, int K, int N, int mode, float* t) {
;     const int tid = opaque_tid(), ntn = N >> 6, ntiles = (K >> 7) * ntn;
;     const int lk = tid >> 4, ln4 = (tid & 15) * 4;
;     float4 pv[4];
;     ...
;     int tile = blockIdx.x;
;     if (tile < ntiles) CVT_LOAD(tile);
; __device__ __forceinline__ void phase_convert(const Params& p, unsigned char* smem) {
;     ...
;     for (int l = 0; l < 2; ++l) {
;         for (int f = 0; f < 2; ++f) {
;             const size_t wo = (size_t)(l * 2 + f) * 2048 * 5632;
;             bf16_t* gu = (bf16_t*)(p.ws + OFF_GU + (size_t)(l * 2 + f) * SZ_GU);
;             convT_job(p.in[3] + wo, gu, 2048, 5632, 1, t);
.LBB0_623:
	v_lshrrev_b32_e32 v6, 6, v234
	v_and_b32_e32 v25, 63, v234
	v_lshrrev_b32_e32 v26, 3, v234
	v_readfirstlane_b32 s46, v6
	v_and_b32_e32 v27, 7, v234
	v_readlane_b32 s54, v255, 28
	v_readlane_b32 s55, v255, 29
	s_lshl_b32 s46, s46, 12
	v_lshrrev_b32_e32 v28, 2, v26
	v_xor_b32_e32 v28, v28, v27
	v_lshlrev_b32_e32 v28, 4, v28
	v_and_b32_e32 v29, 3, v26
	v_lshl_or_b32 v28, v29, 2, v28
	v_lshl_or_b32 v4, v27, 12, v28
	v_lshrrev_b32_e32 v30, 4, v25
	v_lshl_add_u32 v30, v6, 4, v30
	v_and_b32_e32 v31, 15, v25
	v_xor_b32_e32 v31, v31, v6
	v_lshlrev_b32_e32 v31, 4, v31
	v_lshlrev_b32_e32 v27, 5, v27
	s_mov_b32 s40, s60
	s_cmp_lt_u32 s40, 2816
	s_cbranch_scc0 .Lcv_gate_skip
	v_mov_b32_e32 v29, 0x5800
	v_mov_b32_e32 v28, 0x1000
	v_mad_u32_u24 v0, v30, v29, v31
	v_mad_u32_u24 v5, v26, v28, v27
	v_add_u32_e32 v1, 0x16000, v0
	v_add_u32_e32 v2, 0x2c000, v0
	v_add_u32_e32 v3, 0x42000, v0
	s_barrier
	s_mov_b32 s41, 0
	s_mov_b32 s47, s40
	s_mov_b32 s48, s46
	s_mul_hi_u32 s0, s47, 0x2e8ba3
	s_mul_i32 s1, s0, 1408
	s_sub_u32 s1, s47, s1
	s_mul_hi_u32 s2, s1, 0x2e8ba2f
	s_mul_i32 s8, s2, 88
	s_sub_u32 s8, s1, s8
	s_mul_i32 s9, s0, 0x5800000
	s_mul_i32 s28, s2, 0x2c0000
	s_add_u32 s9, s9, s28
	s_lshl_b32 s8, s8, 8
	s_add_u32 s9, s9, s8
	s_add_u32 s42, s70, s9
	s_addc_u32 s43, s71, 0
	s_mov_b32 m0, s48
	s_add_u32 s49, s48, 0x400
	global_load_lds_dwordx4 v0, s[42:43]
	s_mov_b32 m0, s49
	s_add_u32 s49, s48, 0x800
	global_load_lds_dwordx4 v1, s[42:43]
	s_mov_b32 m0, s49
	s_add_u32 s49, s48, 0xc00
	global_load_lds_dwordx4 v2, s[42:43]
	s_mov_b32 m0, s49
	s_nop 0
	global_load_lds_dwordx4 v3, s[42:43]
	global_load_dword v24, v173, s[70:71]
	global_load_dword v24, v173, s[70:71]
	s_add_u32 s47, s40, 256
	s_add_u32 s48, s46, 0x8000
	s_cmp_lt_u32 s47, 2816
	s_cbranch_scc0 .Lcv_gate_pd1
	s_mul_hi_u32 s0, s47, 0x2e8ba3
	s_mul_i32 s1, s0, 1408
	s_sub_u32 s1, s47, s1
	s_mul_hi_u32 s2, s1, 0x2e8ba2f
	s_mul_i32 s8, s2, 88
	s_sub_u32 s8, s1, s8
	s_mul_i32 s9, s0, 0x5800000
	s_mul_i32 s28, s2, 0x2c0000
	s_add_u32 s9, s9, s28
	s_lshl_b32 s8, s8, 8
	s_add_u32 s9, s9, s8
	s_add_u32 s42, s70, s9
	s_addc_u32 s43, s71, 0
	s_mov_b32 m0, s48
	s_add_u32 s49, s48, 0x400
	global_load_lds_dwordx4 v0, s[42:43]
	s_mov_b32 m0, s49
	s_add_u32 s49, s48, 0x800
	global_load_lds_dwordx4 v1, s[42:43]
	s_mov_b32 m0, s49
	s_add_u32 s49, s48, 0xc00
	global_load_lds_dwordx4 v2, s[42:43]
	s_mov_b32 m0, s49
	s_nop 0
	global_load_lds_dwordx4 v3, s[42:43]
	s_branch .Lcv_gate_pj1

; #define CVT_LOAD(tile_) do { const int k0_ = ((tile_) / ntn) << 7, n0_ = ((tile_) % ntn) << 6; \
;         _Pragma("unroll") for (int pp = 0; pp < 4; ++pp) pv[pp] = *(const float4*)(src + (size_t)(k0_ + lk + 32 * pp) * N + n0_ + ln4); } while (0)
; __device__ __forceinline__ void convT_job(const float* __restrict__ src, bf16_t* __restrict__ dst, int K, int N, int mode, float* t) {
;     ...
;         if (tile + (int)gridDim.x < ntiles) CVT_LOAD(tile + (int)gridDim.x);
.Lcv_gate_pj1:
	global_load_dword v24, v173, s[70:71]
	global_load_dword v24, v173, s[70:71]
	s_add_u32 s47, s40, 512
	s_add_u32 s48, s46, 0x10000
	s_cmp_lt_u32 s47, 2816
	s_cbranch_scc0 .Lcv_gate_pd2
	s_mul_hi_u32 s0, s47, 0x2e8ba3
	s_mul_i32 s1, s0, 1408
	s_sub_u32 s1, s47, s1
	s_mul_hi_u32 s2, s1, 0x2e8ba2f
	s_mul_i32 s8, s2, 88
	s_sub_u32 s8, s1, s8
	s_mul_i32 s9, s0, 0x5800000
	s_mul_i32 s28, s2, 0x2c0000
	s_add_u32 s9, s9, s28
	s_lshl_b32 s8, s8, 8
	s_add_u32 s9, s9, s8
	s_add_u32 s42, s70, s9
	s_addc_u32 s43, s71, 0
	s_mov_b32 m0, s48
	s_add_u32 s49, s48, 0x400
	global_load_lds_dwordx4 v0, s[42:43]
	s_mov_b32 m0, s49
	s_add_u32 s49, s48, 0x800
	global_load_lds_dwordx4 v1, s[42:43]
	s_mov_b32 m0, s49
	s_add_u32 s49, s48, 0xc00
	global_load_lds_dwordx4 v2, s[42:43]
	s_mov_b32 m0, s49
	s_nop 0
	global_load_lds_dwordx4 v3, s[42:43]
	s_branch .Lcv_gate_pj2

; #define CVT_LOAD(tile_) do { const int k0_ = ((tile_) / ntn) << 7, n0_ = ((tile_) % ntn) << 6; \
;         _Pragma("unroll") for (int pp = 0; pp < 4; ++pp) pv[pp] = *(const float4*)(src + (size_t)(k0_ + lk + 32 * pp) * N + n0_ + ln4); } while (0)
; __device__ __forceinline__ void convT_job(const float* __restrict__ src, bf16_t* __restrict__ dst, int K, int N, int mode, float* t) {
;     ...
; #pragma unroll 1
;     for (; tile < ntiles; tile += gridDim.x) {
;         const int k0 = (tile / ntn) << 7, n0 = (tile % ntn) << 6;
; #pragma unroll
;         for (int pp = 0; pp < 4; ++pp) { const int k = lk + 32 * pp; t[k * 65 + ln4] = pv[pp].x; t[k * 65 + ln4 + 1] = pv[pp].y; t[k * 65 + ln4 + 2] = pv[pp].z; t[k * 65 + ln4 + 3] = pv[pp].w; }
;         if (tile + (int)gridDim.x < ntiles) CVT_LOAD(tile + (int)gridDim.x);
.Lcv_gate_loop:
	s_waitcnt vmcnt(14)
	s_barrier
	s_add_u32 s47, s40, 768
	s_add_u32 s48, s41, 0x18000
	s_and_b32 s48, s48, 0x1ffff
	s_add_u32 s48, s48, s46
	s_cmp_lt_u32 s47, 2816
	s_cbranch_scc0 .Lcv_gate_ld
	s_mul_hi_u32 s0, s47, 0x2e8ba3
	s_mul_i32 s1, s0, 1408
	s_sub_u32 s1, s47, s1
	s_mul_hi_u32 s2, s1, 0x2e8ba2f
	s_mul_i32 s8, s2, 88
	s_sub_u32 s8, s1, s8
	s_mul_i32 s9, s0, 0x5800000
	s_mul_i32 s28, s2, 0x2c0000
	s_add_u32 s9, s9, s28
	s_lshl_b32 s8, s8, 8
	s_add_u32 s9, s9, s8
	s_add_u32 s42, s70, s9
	s_addc_u32 s43, s71, 0
	s_mov_b32 m0, s48
	s_add_u32 s49, s48, 0x400
	global_load_lds_dwordx4 v0, s[42:43]
	s_mov_b32 m0, s49
	s_add_u32 s49, s48, 0x800
	global_load_lds_dwordx4 v1, s[42:43]
	s_mov_b32 m0, s49
	s_add_u32 s49, s48, 0xc00
	global_load_lds_dwordx4 v2, s[42:43]
	s_mov_b32 m0, s49
	s_nop 0
	global_load_lds_dwordx4 v3, s[42:43]
	s_branch .Lcv_gate_lj

; __device__ __forceinline__ unsigned cvt_pk_bf16(float lo, float hi) { unsigned r; asm volatile("v_cvt_pk_bf16_f32 %0, %1, %2" : "=v"(r) : "v"(lo), "v"(hi)); return r; }
; __device__ __forceinline__ void lds_barrier() { asm volatile("s_waitcnt lgkmcnt(0)" ::: "memory"); __builtin_amdgcn_s_barrier(); asm volatile("" ::: "memory"); }
; __device__ __forceinline__ void convT_job(const float* __restrict__ src, bf16_t* __restrict__ dst, int K, int N, int mode, float* t) {
;     ...
;         lds_barrier();
;         const int n = tid >> 3, k16 = (tid & 7) * 16;
;         float v[16];
; #pragma unroll
;         for (int j = 0; j < 16; ++j) v[j] = t[(k16 + j) * 65 + n];
;         const int nn = n0 + n;
;         const int row = mode == 0 ? nn : (256 * (nn >> 7) + (nn & 127) + (mode == 2 ? 128 : 0));
;         u32x4 w0, w1; w0.x = cvt_pk_bf16(v[0], v[1]); w0.y = cvt_pk_bf16(v[2], v[3]); w0.z = cvt_pk_bf16(v[4], v[5]); w0.w = cvt_pk_bf16(v[6], v[7]);
;         w1.x = cvt_pk_bf16(v[8], v[9]); w1.y = cvt_pk_bf16(v[10], v[11]); w1.z = cvt_pk_bf16(v[12], v[13]); w1.w = cvt_pk_bf16(v[14], v[15]);
;         bf16_t* d = dst + (size_t)row * K + k0 + k16;
;         *(u32x4*)d = w0; *(u32x4*)(d + 8) = w1;
;         lds_barrier();
; __device__ __forceinline__ void phase_convert(const Params& p, unsigned char* smem) {
;     ...
;             convT_job(p.in[3] + wo, gu, 2048, 5632, 1, t);
;             convT_job(p.in[4] + wo, gu, 2048, 5632, 2, t);
.Lcv_gate_lj:
	v_add_u32_e32 v7, s41, v4
	ds_read2st64_b32 v[8:9], v7 offset0:0 offset1:1
	ds_read2st64_b32 v[10:11], v7 offset0:2 offset1:3
	ds_read2st64_b32 v[12:13], v7 offset0:4 offset1:5
	ds_read2st64_b32 v[14:15], v7 offset0:6 offset1:7
	ds_read2st64_b32 v[16:17], v7 offset0:8 offset1:9
	ds_read2st64_b32 v[18:19], v7 offset0:10 offset1:11
	ds_read2st64_b32 v[20:21], v7 offset0:12 offset1:13
	ds_read2st64_b32 v[22:23], v7 offset0:14 offset1:15
	s_mul_hi_u32 s0, s40, 0x2e8ba3
	s_mul_i32 s1, s0, 1408
	s_sub_u32 s1, s40, s1
	s_mul_hi_u32 s2, s1, 0x2e8ba2f
	s_mul_i32 s8, s2, 88
	s_sub_u32 s8, s1, s8
	s_lshr_b32 s9, s8, 1
	s_lshl_b32 s9, s9, 8
	s_and_b32 s28, s8, 1
	s_lshl_b32 s28, s28, 6
	s_add_u32 s9, s9, s28
	s_mul_i32 s9, s9, 0x1000
	s_mul_i32 s28, s0, 0x5800000
	s_add_u32 s9, s9, s28
	s_lshl_b32 s2, s2, 8
	s_add_u32 s9, s9, s2
	s_add_u32 s9, s9, 0x8000
	s_add_u32 s44, s54, s9
	s_addc_u32 s45, s55, 0
	s_waitcnt lgkmcnt(6)
	v_cvt_pk_bf16_f32 v8, v8, v9
	v_cvt_pk_bf16_f32 v9, v10, v11
	s_waitcnt lgkmcnt(4)
	v_cvt_pk_bf16_f32 v10, v12, v13
	v_cvt_pk_bf16_f32 v11, v14, v15
	s_waitcnt lgkmcnt(2)
	v_cvt_pk_bf16_f32 v12, v16, v17
	v_cvt_pk_bf16_f32 v13, v18, v19
	s_waitcnt lgkmcnt(0)
	v_cvt_pk_bf16_f32 v14, v20, v21
	v_cvt_pk_bf16_f32 v15, v22, v23
	global_store_dwordx4 v5, v[8:11], s[44:45]
	global_store_dwordx4 v5, v[12:15], s[44:45] offset:16
	s_add_u32 s40, s40, 256
	s_add_u32 s41, s41, 0x8000
	s_and_b32 s41, s41, 0x1ffff
	s_cmp_lt_u32 s40, 2816
	s_cbranch_scc1 .Lcv_gate_loop
.Lcv_gate_skip:
	s_mov_b32 s40, s60
	s_cmp_lt_u32 s40, 2816
	s_cbranch_scc0 .Lcv_up_skip
	v_mov_b32_e32 v29, 0x5800
	v_mov_b32_e32 v28, 0x1000
	v_mad_u32_u24 v0, v30, v29, v31
	v_mad_u32_u24 v5, v26, v28, v27
	v_add_u32_e32 v1, 0x16000, v0
	v_add_u32_e32 v2, 0x2c000, v0
	v_add_u32_e32 v3, 0x42000, v0
	s_barrier
	s_mov_b32 s41, 0
	s_mov_b32 s47, s40
	s_mov_b32 s48, s46
	s_mul_hi_u32 s0, s47, 0x2e8ba3
	s_mul_i32 s1, s0, 1408
	s_sub_u32 s1, s47, s1
	s_mul_hi_u32 s2, s1, 0x2e8ba2f
	s_mul_i32 s8, s2, 88
	s_sub_u32 s8, s1, s8
	s_mul_i32 s9, s0, 0x5800000
	s_mul_i32 s28, s2, 0x2c0000
	s_add_u32 s9, s9, s28
	s_lshl_b32 s8, s8, 8
	s_add_u32 s9, s9, s8
	s_add_u32 s42, s72, s9
	s_addc_u32 s43, s73, 0
	s_mov_b32 m0, s48
	s_add_u32 s49, s48, 0x400
	global_load_lds_dwordx4 v0, s[42:43]
	s_mov_b32 m0, s49
	s_add_u32 s49, s48, 0x800
	global_load_lds_dwordx4 v1, s[42:43]
	s_mov_b32 m0, s49
	s_add_u32 s49, s48, 0xc00
	global_load_lds_dwordx4 v2, s[42:43]
	s_mov_b32 m0, s49
	s_nop 0
	global_load_lds_dwordx4 v3, s[42:43]
	global_load_dword v24, v173, s[72:73]
	global_load_dword v24, v173, s[72:73]
	s_add_u32 s47, s40, 256
	s_add_u32 s48, s46, 0x8000
	s_cmp_lt_u32 s47, 2816
	s_cbranch_scc0 .Lcv_up_pd1
	s_mul_hi_u32 s0, s47, 0x2e8ba3
	s_mul_i32 s1, s0, 1408
	s_sub_u32 s1, s47, s1
	s_mul_hi_u32 s2, s1, 0x2e8ba2f
	s_mul_i32 s8, s2, 88
	s_sub_u32 s8, s1, s8
	s_mul_i32 s9, s0, 0x5800000
	s_mul_i32 s28, s2, 0x2c0000
	s_add_u32 s9, s9, s28
	s_lshl_b32 s8, s8, 8
	s_add_u32 s9, s9, s8
	s_add_u32 s42, s72, s9
	s_addc_u32 s43, s73, 0
	s_mov_b32 m0, s48
	s_add_u32 s49, s48, 0x400
	global_load_lds_dwordx4 v0, s[42:43]
	s_mov_b32 m0, s49
	s_add_u32 s49, s48, 0x800
	global_load_lds_dwordx4 v1, s[42:43]
	s_mov_b32 m0, s49
	s_add_u32 s49, s48, 0xc00
	global_load_lds_dwordx4 v2, s[42:43]
	s_mov_b32 m0, s49
	s_nop 0
	global_load_lds_dwordx4 v3, s[42:43]
	s_branch .Lcv_up_pj1

; #define CVT_LOAD(tile_) do { const int k0_ = ((tile_) / ntn) << 7, n0_ = ((tile_) % ntn) << 6; \
;         _Pragma("unroll") for (int pp = 0; pp < 4; ++pp) pv[pp] = *(const float4*)(src + (size_t)(k0_ + lk + 32 * pp) * N + n0_ + ln4); } while (0)
; __device__ __forceinline__ void convT_job(const float* __restrict__ src, bf16_t* __restrict__ dst, int K, int N, int mode, float* t) {
;     ...
;         if (tile + (int)gridDim.x < ntiles) CVT_LOAD(tile + (int)gridDim.x);
.Lcv_up_pj1:
	global_load_dword v24, v173, s[72:73]
	global_load_dword v24, v173, s[72:73]
	s_add_u32 s47, s40, 512
	s_add_u32 s48, s46, 0x10000
	s_cmp_lt_u32 s47, 2816
	s_cbranch_scc0 .Lcv_up_pd2
	s_mul_hi_u32 s0, s47, 0x2e8ba3
	s_mul_i32 s1, s0, 1408
	s_sub_u32 s1, s47, s1
	s_mul_hi_u32 s2, s1, 0x2e8ba2f
	s_mul_i32 s8, s2, 88
	s_sub_u32 s8, s1, s8
	s_mul_i32 s9, s0, 0x5800000
	s_mul_i32 s28, s2, 0x2c0000
	s_add_u32 s9, s9, s28
	s_lshl_b32 s8, s8, 8
	s_add_u32 s9, s9, s8
	s_add_u32 s42, s72, s9
	s_addc_u32 s43, s73, 0
	s_mov_b32 m0, s48
	s_add_u32 s49, s48, 0x400
	global_load_lds_dwordx4 v0, s[42:43]
	s_mov_b32 m0, s49
	s_add_u32 s49, s48, 0x800
	global_load_lds_dwordx4 v1, s[42:43]
	s_mov_b32 m0, s49
	s_add_u32 s49, s48, 0xc00
	global_load_lds_dwordx4 v2, s[42:43]
	s_mov_b32 m0, s49
	s_nop 0
	global_load_lds_dwordx4 v3, s[42:43]
	s_branch .Lcv_up_pj2

; #define CVT_LOAD(tile_) do { const int k0_ = ((tile_) / ntn) << 7, n0_ = ((tile_) % ntn) << 6; \
;         _Pragma("unroll") for (int pp = 0; pp < 4; ++pp) pv[pp] = *(const float4*)(src + (size_t)(k0_ + lk + 32 * pp) * N + n0_ + ln4); } while (0)
; __device__ __forceinline__ void convT_job(const float* __restrict__ src, bf16_t* __restrict__ dst, int K, int N, int mode, float* t) {
;     ...
; #pragma unroll 1
;     for (; tile < ntiles; tile += gridDim.x) {
;         const int k0 = (tile / ntn) << 7, n0 = (tile % ntn) << 6;
; #pragma unroll
;         for (int pp = 0; pp < 4; ++pp) { const int k = lk + 32 * pp; t[k * 65 + ln4] = pv[pp].x; t[k * 65 + ln4 + 1] = pv[pp].y; t[k * 65 + ln4 + 2] = pv[pp].z; t[k * 65 + ln4 + 3] = pv[pp].w; }
;         if (tile + (int)gridDim.x < ntiles) CVT_LOAD(tile + (int)gridDim.x);
.Lcv_up_loop:
	s_waitcnt vmcnt(14)
	s_barrier
	s_add_u32 s47, s40, 768
	s_add_u32 s48, s41, 0x18000
	s_and_b32 s48, s48, 0x1ffff
	s_add_u32 s48, s48, s46
	s_cmp_lt_u32 s47, 2816
	s_cbranch_scc0 .Lcv_up_ld
	s_mul_hi_u32 s0, s47, 0x2e8ba3
	s_mul_i32 s1, s0, 1408
	s_sub_u32 s1, s47, s1
	s_mul_hi_u32 s2, s1, 0x2e8ba2f
	s_mul_i32 s8, s2, 88
	s_sub_u32 s8, s1, s8
	s_mul_i32 s9, s0, 0x5800000
	s_mul_i32 s28, s2, 0x2c0000
	s_add_u32 s9, s9, s28
	s_lshl_b32 s8, s8, 8
	s_add_u32 s9, s9, s8
	s_add_u32 s42, s72, s9
	s_addc_u32 s43, s73, 0
	s_mov_b32 m0, s48
	s_add_u32 s49, s48, 0x400
	global_load_lds_dwordx4 v0, s[42:43]
	s_mov_b32 m0, s49
	s_add_u32 s49, s48, 0x800
	global_load_lds_dwordx4 v1, s[42:43]
	s_mov_b32 m0, s49
	s_add_u32 s49, s48, 0xc00
	global_load_lds_dwordx4 v2, s[42:43]
	s_mov_b32 m0, s49
	s_nop 0
	global_load_lds_dwordx4 v3, s[42:43]
	s_branch .Lcv_up_lj

; __device__ __forceinline__ unsigned cvt_pk_bf16(float lo, float hi) { unsigned r; asm volatile("v_cvt_pk_bf16_f32 %0, %1, %2" : "=v"(r) : "v"(lo), "v"(hi)); return r; }
; __device__ __forceinline__ void lds_barrier() { asm volatile("s_waitcnt lgkmcnt(0)" ::: "memory"); __builtin_amdgcn_s_barrier(); asm volatile("" ::: "memory"); }
; __device__ __forceinline__ void convT_job(const float* __restrict__ src, bf16_t* __restrict__ dst, int K, int N, int mode, float* t) {
;     ...
;         lds_barrier();
;         const int n = tid >> 3, k16 = (tid & 7) * 16;
;         float v[16];
; #pragma unroll
;         for (int j = 0; j < 16; ++j) v[j] = t[(k16 + j) * 65 + n];
;         const int nn = n0 + n;
;         const int row = mode == 0 ? nn : (256 * (nn >> 7) + (nn & 127) + (mode == 2 ? 128 : 0));
;         u32x4 w0, w1; w0.x = cvt_pk_bf16(v[0], v[1]); w0.y = cvt_pk_bf16(v[2], v[3]); w0.z = cvt_pk_bf16(v[4], v[5]); w0.w = cvt_pk_bf16(v[6], v[7]);
;         w1.x = cvt_pk_bf16(v[8], v[9]); w1.y = cvt_pk_bf16(v[10], v[11]); w1.z = cvt_pk_bf16(v[12], v[13]); w1.w = cvt_pk_bf16(v[14], v[15]);
;         bf16_t* d = dst + (size_t)row * K + k0 + k16;
;         *(u32x4*)d = w0; *(u32x4*)(d + 8) = w1;
;         lds_barrier();
; __device__ __forceinline__ void phase_convert(const Params& p, unsigned char* smem) {
;     ...
;             convT_job(p.in[5] + wo, (bf16_t*)(p.ws + OFF_DN + (size_t)(l * 2 + f) * SZ_DN), 5632, 2048, 0, t);
.Lcv_up_lj:
	v_add_u32_e32 v7, s41, v4
	ds_read2st64_b32 v[8:9], v7 offset0:0 offset1:1
	ds_read2st64_b32 v[10:11], v7 offset0:2 offset1:3
	ds_read2st64_b32 v[12:13], v7 offset0:4 offset1:5
	ds_read2st64_b32 v[14:15], v7 offset0:6 offset1:7
	ds_read2st64_b32 v[16:17], v7 offset0:8 offset1:9
	ds_read2st64_b32 v[18:19], v7 offset0:10 offset1:11
	ds_read2st64_b32 v[20:21], v7 offset0:12 offset1:13
	ds_read2st64_b32 v[22:23], v7 offset0:14 offset1:15
	s_mul_hi_u32 s0, s40, 0x2e8ba3
	s_mul_i32 s1, s0, 1408
	s_sub_u32 s1, s40, s1
	s_mul_hi_u32 s2, s1, 0x2e8ba2f
	s_mul_i32 s8, s2, 88
	s_sub_u32 s8, s1, s8
	s_lshr_b32 s9, s8, 1
	s_lshl_b32 s9, s9, 8
	s_and_b32 s28, s8, 1
	s_lshl_b32 s28, s28, 6
	s_add_u32 s9, s9, s28
	s_add_u32 s9, s9, 128
	s_mul_i32 s9, s9, 0x1000
	s_mul_i32 s28, s0, 0x5800000
	s_add_u32 s9, s9, s28
	s_lshl_b32 s2, s2, 8
	s_add_u32 s9, s9, s2
	s_add_u32 s9, s9, 0x8000
	s_add_u32 s44, s54, s9
	s_addc_u32 s45, s55, 0
	s_waitcnt lgkmcnt(6)
	v_cvt_pk_bf16_f32 v8, v8, v9
	v_cvt_pk_bf16_f32 v9, v10, v11
	s_waitcnt lgkmcnt(4)
	v_cvt_pk_bf16_f32 v10, v12, v13
	v_cvt_pk_bf16_f32 v11, v14, v15
	s_waitcnt lgkmcnt(2)
	v_cvt_pk_bf16_f32 v12, v16, v17
	v_cvt_pk_bf16_f32 v13, v18, v19
	s_waitcnt lgkmcnt(0)
	v_cvt_pk_bf16_f32 v14, v20, v21
	v_cvt_pk_bf16_f32 v15, v22, v23
	global_store_dwordx4 v5, v[8:11], s[44:45]
	global_store_dwordx4 v5, v[12:15], s[44:45] offset:16
	s_add_u32 s40, s40, 256
	s_add_u32 s41, s41, 0x8000
	s_and_b32 s41, s41, 0x1ffff
	s_cmp_lt_u32 s40, 2816
	s_cbranch_scc1 .Lcv_up_loop
.Lcv_up_skip:
	s_mov_b32 s40, s60
	s_cmp_lt_u32 s40, 2816
	s_cbranch_scc0 .Lcv_down_skip
	v_mov_b32_e32 v29, 0x2000
	v_mov_b32_e32 v28, 0x2c00
	v_mad_u32_u24 v0, v30, v29, v31
	v_mad_u32_u24 v5, v26, v28, v27
	v_add_u32_e32 v1, 0x8000, v0
	v_add_u32_e32 v2, 0x10000, v0
	v_add_u32_e32 v3, 0x18000, v0
	s_barrier
	s_mov_b32 s41, 0
	s_mov_b32 s47, s40
	s_mov_b32 s48, s46
	s_mul_hi_u32 s0, s47, 0x2e8ba3
	s_mul_i32 s1, s0, 1408
	s_sub_u32 s1, s47, s1
	s_mul_hi_u32 s2, s1, 0x8000001
	s_mul_i32 s8, s2, 32
	s_sub_u32 s8, s1, s8
	s_mul_i32 s9, s0, 0x5800000
	s_mul_i32 s28, s2, 0x100000
	s_add_u32 s9, s9, s28
	s_lshl_b32 s8, s8, 8
	s_add_u32 s9, s9, s8
	s_add_u32 s42, s74, s9
	s_addc_u32 s43, s75, 0
	s_mov_b32 m0, s48
	s_add_u32 s49, s48, 0x400
	global_load_lds_dwordx4 v0, s[42:43]
	s_mov_b32 m0, s49
	s_add_u32 s49, s48, 0x800
	global_load_lds_dwordx4 v1, s[42:43]
	s_mov_b32 m0, s49
	s_add_u32 s49, s48, 0xc00
	global_load_lds_dwordx4 v2, s[42:43]
	s_mov_b32 m0, s49
	s_nop 0
	global_load_lds_dwordx4 v3, s[42:43]
	global_load_dword v24, v173, s[74:75]
	global_load_dword v24, v173, s[74:75]
	s_add_u32 s47, s40, 256
	s_add_u32 s48, s46, 0x8000
	s_cmp_lt_u32 s47, 2816
	s_cbranch_scc0 .Lcv_down_pd1
	s_mul_hi_u32 s0, s47, 0x2e8ba3
	s_mul_i32 s1, s0, 1408
	s_sub_u32 s1, s47, s1
	s_mul_hi_u32 s2, s1, 0x8000001
	s_mul_i32 s8, s2, 32
	s_sub_u32 s8, s1, s8
	s_mul_i32 s9, s0, 0x5800000
	s_mul_i32 s28, s2, 0x100000
	s_add_u32 s9, s9, s28
	s_lshl_b32 s8, s8, 8
	s_add_u32 s9, s9, s8
	s_add_u32 s42, s74, s9
	s_addc_u32 s43, s75, 0
	s_mov_b32 m0, s48
	s_add_u32 s49, s48, 0x400
	global_load_lds_dwordx4 v0, s[42:43]
	s_mov_b32 m0, s49
	s_add_u32 s49, s48, 0x800
	global_load_lds_dwordx4 v1, s[42:43]
	s_mov_b32 m0, s49
	s_add_u32 s49, s48, 0xc00
	global_load_lds_dwordx4 v2, s[42:43]
	s_mov_b32 m0, s49
	s_nop 0
	global_load_lds_dwordx4 v3, s[42:43]
	s_branch .Lcv_down_pj1

; #define CVT_LOAD(tile_) do { const int k0_ = ((tile_) / ntn) << 7, n0_ = ((tile_) % ntn) << 6; \
;         _Pragma("unroll") for (int pp = 0; pp < 4; ++pp) pv[pp] = *(const float4*)(src + (size_t)(k0_ + lk + 32 * pp) * N + n0_ + ln4); } while (0)
; __device__ __forceinline__ void convT_job(const float* __restrict__ src, bf16_t* __restrict__ dst, int K, int N, int mode, float* t) {
;     ...
;         if (tile + (int)gridDim.x < ntiles) CVT_LOAD(tile + (int)gridDim.x);
.Lcv_down_pj1:
	global_load_dword v24, v173, s[74:75]
	global_load_dword v24, v173, s[74:75]
	s_add_u32 s47, s40, 512
	s_add_u32 s48, s46, 0x10000
	s_cmp_lt_u32 s47, 2816
	s_cbranch_scc0 .Lcv_down_pd2
	s_mul_hi_u32 s0, s47, 0x2e8ba3
	s_mul_i32 s1, s0, 1408
	s_sub_u32 s1, s47, s1
	s_mul_hi_u32 s2, s1, 0x8000001
	s_mul_i32 s8, s2, 32
	s_sub_u32 s8, s1, s8
	s_mul_i32 s9, s0, 0x5800000
	s_mul_i32 s28, s2, 0x100000
	s_add_u32 s9, s9, s28
	s_lshl_b32 s8, s8, 8
	s_add_u32 s9, s9, s8
	s_add_u32 s42, s74, s9
	s_addc_u32 s43, s75, 0
	s_mov_b32 m0, s48
	s_add_u32 s49, s48, 0x400
	global_load_lds_dwordx4 v0, s[42:43]
	s_mov_b32 m0, s49
	s_add_u32 s49, s48, 0x800
	global_load_lds_dwordx4 v1, s[42:43]
	s_mov_b32 m0, s49
	s_add_u32 s49, s48, 0xc00
	global_load_lds_dwordx4 v2, s[42:43]
	s_mov_b32 m0, s49
	s_nop 0
	global_load_lds_dwordx4 v3, s[42:43]
	s_branch .Lcv_down_pj2

; #define CVT_LOAD(tile_) do { const int k0_ = ((tile_) / ntn) << 7, n0_ = ((tile_) % ntn) << 6; \
;         _Pragma("unroll") for (int pp = 0; pp < 4; ++pp) pv[pp] = *(const float4*)(src + (size_t)(k0_ + lk + 32 * pp) * N + n0_ + ln4); } while (0)
; __device__ __forceinline__ void convT_job(const float* __restrict__ src, bf16_t* __restrict__ dst, int K, int N, int mode, float* t) {
;     ...
; #pragma unroll 1
;     for (; tile < ntiles; tile += gridDim.x) {
;         const int k0 = (tile / ntn) << 7, n0 = (tile % ntn) << 6;
; #pragma unroll
;         for (int pp = 0; pp < 4; ++pp) { const int k = lk + 32 * pp; t[k * 65 + ln4] = pv[pp].x; t[k * 65 + ln4 + 1] = pv[pp].y; t[k * 65 + ln4 + 2] = pv[pp].z; t[k * 65 + ln4 + 3] = pv[pp].w; }
;         if (tile + (int)gridDim.x < ntiles) CVT_LOAD(tile + (int)gridDim.x);
.Lcv_down_loop:
	s_waitcnt vmcnt(14)
	s_barrier
	s_add_u32 s47, s40, 768
	s_add_u32 s48, s41, 0x18000
	s_and_b32 s48, s48, 0x1ffff
	s_add_u32 s48, s48, s46
	s_cmp_lt_u32 s47, 2816
	s_cbranch_scc0 .Lcv_down_ld
	s_mul_hi_u32 s0, s47, 0x2e8ba3
	s_mul_i32 s1, s0, 1408
	s_sub_u32 s1, s47, s1
	s_mul_hi_u32 s2, s1, 0x8000001
	s_mul_i32 s8, s2, 32
	s_sub_u32 s8, s1, s8
	s_mul_i32 s9, s0, 0x5800000
	s_mul_i32 s28, s2, 0x100000
	s_add_u32 s9, s9, s28
	s_lshl_b32 s8, s8, 8
	s_add_u32 s9, s9, s8
	s_add_u32 s42, s74, s9
	s_addc_u32 s43, s75, 0
	s_mov_b32 m0, s48
	s_add_u32 s49, s48, 0x400
	global_load_lds_dwordx4 v0, s[42:43]
	s_mov_b32 m0, s49
	s_add_u32 s49, s48, 0x800
	global_load_lds_dwordx4 v1, s[42:43]
	s_mov_b32 m0, s49
	s_add_u32 s49, s48, 0xc00
	global_load_lds_dwordx4 v2, s[42:43]
	s_mov_b32 m0, s49
	s_nop 0
	global_load_lds_dwordx4 v3, s[42:43]
	s_branch .Lcv_down_lj

; __device__ __forceinline__ unsigned cvt_pk_bf16(float lo, float hi) { unsigned r; asm volatile("v_cvt_pk_bf16_f32 %0, %1, %2" : "=v"(r) : "v"(lo), "v"(hi)); return r; }
; __device__ __forceinline__ void lds_barrier() { asm volatile("s_waitcnt lgkmcnt(0)" ::: "memory"); __builtin_amdgcn_s_barrier(); asm volatile("" ::: "memory"); }
; __device__ __forceinline__ void convT_job(const float* __restrict__ src, bf16_t* __restrict__ dst, int K, int N, int mode, float* t) {
;     ...
;         lds_barrier();
;         const int n = tid >> 3, k16 = (tid & 7) * 16;
;         float v[16];
; #pragma unroll
;         for (int j = 0; j < 16; ++j) v[j] = t[(k16 + j) * 65 + n];
;         const int nn = n0 + n;
;         const int row = mode == 0 ? nn : (256 * (nn >> 7) + (nn & 127) + (mode == 2 ? 128 : 0));
;         u32x4 w0, w1; w0.x = cvt_pk_bf16(v[0], v[1]); w0.y = cvt_pk_bf16(v[2], v[3]); w0.z = cvt_pk_bf16(v[4], v[5]); w0.w = cvt_pk_bf16(v[6], v[7]);
;         w1.x = cvt_pk_bf16(v[8], v[9]); w1.y = cvt_pk_bf16(v[10], v[11]); w1.z = cvt_pk_bf16(v[12], v[13]); w1.w = cvt_pk_bf16(v[14], v[15]);
;         bf16_t* d = dst + (size_t)row * K + k0 + k16;
;         *(u32x4*)d = w0; *(u32x4*)(d + 8) = w1;
;         lds_barrier();
.Lcv_down_lj:
	v_add_u32_e32 v7, s41, v4
	ds_read2st64_b32 v[8:9], v7 offset0:0 offset1:1
	ds_read2st64_b32 v[10:11], v7 offset0:2 offset1:3
	ds_read2st64_b32 v[12:13], v7 offset0:4 offset1:5
	ds_read2st64_b32 v[14:15], v7 offset0:6 offset1:7
	ds_read2st64_b32 v[16:17], v7 offset0:8 offset1:9
	ds_read2st64_b32 v[18:19], v7 offset0:10 offset1:11
	ds_read2st64_b32 v[20:21], v7 offset0:12 offset1:13
	ds_read2st64_b32 v[22:23], v7 offset0:14 offset1:15
	s_mul_hi_u32 s0, s40, 0x2e8ba3
	s_mul_i32 s1, s0, 1408
	s_sub_u32 s1, s40, s1
	s_mul_hi_u32 s2, s1, 0x8000001
	s_mul_i32 s8, s2, 32
	s_sub_u32 s8, s1, s8
	s_lshl_b32 s9, s8, 6
	s_mul_i32 s9, s9, 0x2c00
	s_mul_i32 s28, s0, 0x2c00000
	s_add_u32 s9, s9, s28
	s_lshl_b32 s2, s2, 8
	s_add_u32 s9, s9, s2
	s_add_u32 s9, s9, 0xb008000
	s_add_u32 s44, s54, s9
	s_addc_u32 s45, s55, 0
	s_waitcnt lgkmcnt(6)
	v_cvt_pk_bf16_f32 v8, v8, v9
	v_cvt_pk_bf16_f32 v9, v10, v11
	s_waitcnt lgkmcnt(4)
	v_cvt_pk_bf16_f32 v10, v12, v13
	v_cvt_pk_bf16_f32 v11, v14, v15
	s_waitcnt lgkmcnt(2)
	v_cvt_pk_bf16_f32 v12, v16, v17
	v_cvt_pk_bf16_f32 v13, v18, v19
	s_waitcnt lgkmcnt(0)
	v_cvt_pk_bf16_f32 v14, v20, v21
	v_cvt_pk_bf16_f32 v15, v22, v23
	global_store_dwordx4 v5, v[8:11], s[44:45]
	global_store_dwordx4 v5, v[12:15], s[44:45] offset:16
	s_add_u32 s40, s40, 256
	s_add_u32 s41, s41, 0x8000
	s_and_b32 s41, s41, 0x1ffff
	s_cmp_lt_u32 s40, 2816
	s_cbranch_scc1 .Lcv_down_loop

; __device__ __forceinline__ unsigned cvt_pk_bf16(float lo, float hi) { unsigned r; asm volatile("v_cvt_pk_bf16_f32 %0, %1, %2" : "=v"(r) : "v"(lo), "v"(hi)); return r; }
; __device__ __forceinline__ void lds_barrier() { asm volatile("s_waitcnt lgkmcnt(0)" ::: "memory"); __builtin_amdgcn_s_barrier(); asm volatile("" ::: "memory"); }
; __device__ __forceinline__ void convT_job(const float* __restrict__ src, bf16_t* __restrict__ dst, int K, int N, int mode, float* t) {
;     ...
;         lds_barrier();
;         const int n = tid >> 3, k16 = (tid & 7) * 16;
;         float v[16];
; #pragma unroll
;         for (int j = 0; j < 16; ++j) v[j] = t[(k16 + j) * 65 + n];
;         const int nn = n0 + n;
;         const int row = mode == 0 ? nn : (256 * (nn >> 7) + (nn & 127) + (mode == 2 ? 128 : 0));
;         u32x4 w0, w1; w0.x = cvt_pk_bf16(v[0], v[1]); w0.y = cvt_pk_bf16(v[2], v[3]); w0.z = cvt_pk_bf16(v[4], v[5]); w0.w = cvt_pk_bf16(v[6], v[7]);
;         w1.x = cvt_pk_bf16(v[8], v[9]); w1.y = cvt_pk_bf16(v[10], v[11]); w1.z = cvt_pk_bf16(v[12], v[13]); w1.w = cvt_pk_bf16(v[14], v[15]);
;         bf16_t* d = dst + (size_t)row * K + k0 + k16;
;         *(u32x4*)d = w0; *(u32x4*)(d + 8) = w1;
;         lds_barrier();
; __device__ __forceinline__ void phase_convert(const Params& p, unsigned char* smem) {
;     ...
;         convT_job(p.in[6] + (size_t)l * 2048 * 5632, (bf16_t*)(p.ws + OFF_IN + (size_t)l * SZ_IN), 2048, 5632, 0, t);
;         convT_job(p.in[7] + (size_t)l * 2048 * 2048, (bf16_t*)(p.ws + OFF_OUT + (size_t)l * SZ_OUT), 2048, 2048, 0, t);
;         for (int g = 0; g < 4; ++g) {
;             convT_job(p.in[10] + (size_t)(l * 4 + g) * 16384, (bf16_t*)(p.ws + OFF_RGA + (size_t)l * SZ_RG) + g * 16384, 128, 128, 0, t);
.Lcv_win_lj:
	v_add_u32_e32 v7, s41, v4
	ds_read2st64_b32 v[8:9], v7 offset0:0 offset1:1
	ds_read2st64_b32 v[10:11], v7 offset0:2 offset1:3
	ds_read2st64_b32 v[12:13], v7 offset0:4 offset1:5
	ds_read2st64_b32 v[14:15], v7 offset0:6 offset1:7
	ds_read2st64_b32 v[16:17], v7 offset0:8 offset1:9
	ds_read2st64_b32 v[18:19], v7 offset0:10 offset1:11
	ds_read2st64_b32 v[20:21], v7 offset0:12 offset1:13
	ds_read2st64_b32 v[22:23], v7 offset0:14 offset1:15
	s_mul_hi_u32 s0, s40, 0x2e8ba3
	s_mul_i32 s1, s0, 1408
	s_sub_u32 s1, s40, s1
	s_mul_hi_u32 s2, s1, 0x2e8ba2f
	s_mul_i32 s8, s2, 88
	s_sub_u32 s8, s1, s8
	s_lshl_b32 s9, s8, 6
	s_mul_i32 s9, s9, 0x1000
	s_mul_i32 s28, s0, 0x1600000
	s_add_u32 s9, s9, s28
	s_lshl_b32 s2, s2, 8
	s_add_u32 s9, s9, s2
	s_add_u32 s9, s9, 0x10808000
	s_add_u32 s44, s54, s9
	s_addc_u32 s45, s55, 0
	s_waitcnt lgkmcnt(6)
	v_cvt_pk_bf16_f32 v8, v8, v9
	v_cvt_pk_bf16_f32 v9, v10, v11
	s_waitcnt lgkmcnt(4)
	v_cvt_pk_bf16_f32 v10, v12, v13
	v_cvt_pk_bf16_f32 v11, v14, v15
	s_waitcnt lgkmcnt(2)
	v_cvt_pk_bf16_f32 v12, v16, v17
	v_cvt_pk_bf16_f32 v13, v18, v19
	s_waitcnt lgkmcnt(0)
	v_cvt_pk_bf16_f32 v14, v20, v21
	v_cvt_pk_bf16_f32 v15, v22, v23
	global_store_dwordx4 v5, v[8:11], s[44:45]
	global_store_dwordx4 v5, v[12:15], s[44:45] offset:16
	s_add_u32 s40, s40, 256
	s_add_u32 s41, s41, 0x8000
	s_and_b32 s41, s41, 0x1ffff
	s_cmp_lt_u32 s40, 2816
	s_cbranch_scc1 .Lcv_win_loop
.Lcv_win_skip:
	s_mov_b32 s40, s60
	s_cmp_lt_u32 s40, 16
	s_cbranch_scc0 .Lcv_rga_skip
	v_mov_b32_e32 v29, 0x200
	v_mov_b32_e32 v28, 0x100
	v_mad_u32_u24 v0, v30, v29, v31
	v_mad_u32_u24 v5, v26, v28, v27
	v_add_u32_e32 v1, 0x800, v0
	v_add_u32_e32 v2, 0x1000, v0
	v_add_u32_e32 v3, 0x1800, v0
	s_barrier
	s_mov_b32 s41, 0
	s_mov_b32 s47, s40
	s_mov_b32 s48, s46
	s_mul_hi_u32 s0, s47, 0x80000001
	s_mul_i32 s1, s0, 2
	s_sub_u32 s1, s47, s1
	s_mul_hi_u32 s2, s1, 0x80000001
	s_mul_i32 s8, s2, 2
	s_sub_u32 s8, s1, s8
	s_mul_i32 s9, s0, 0x10000
	s_mul_i32 s28, s2, 0x10000
	s_add_u32 s9, s9, s28
	s_lshl_b32 s8, s8, 8
	s_add_u32 s9, s9, s8
	s_add_u32 s42, s84, s9
	s_addc_u32 s43, s85, 0
	s_mov_b32 m0, s48
	s_add_u32 s49, s48, 0x400
	global_load_lds_dwordx4 v0, s[42:43]
	s_mov_b32 m0, s49
	s_add_u32 s49, s48, 0x800
	global_load_lds_dwordx4 v1, s[42:43]
	s_mov_b32 m0, s49
	s_add_u32 s49, s48, 0xc00
	global_load_lds_dwordx4 v2, s[42:43]
	s_mov_b32 m0, s49
	s_nop 0
	global_load_lds_dwordx4 v3, s[42:43]
	global_load_dword v24, v173, s[84:85]
	global_load_dword v24, v173, s[84:85]
	s_add_u32 s47, s40, 256
	s_add_u32 s48, s46, 0x8000
	s_cmp_lt_u32 s47, 16
	s_cbranch_scc0 .Lcv_rga_pd1
	s_mul_hi_u32 s0, s47, 0x80000001
	s_mul_i32 s1, s0, 2
	s_sub_u32 s1, s47, s1
	s_mul_hi_u32 s2, s1, 0x80000001
	s_mul_i32 s8, s2, 2
	s_sub_u32 s8, s1, s8
	s_mul_i32 s9, s0, 0x10000
	s_mul_i32 s28, s2, 0x10000
	s_add_u32 s9, s9, s28
	s_lshl_b32 s8, s8, 8
	s_add_u32 s9, s9, s8
	s_add_u32 s42, s84, s9
	s_addc_u32 s43, s85, 0
	s_mov_b32 m0, s48
	s_add_u32 s49, s48, 0x400
	global_load_lds_dwordx4 v0, s[42:43]
	s_mov_b32 m0, s49
	s_add_u32 s49, s48, 0x800
	global_load_lds_dwordx4 v1, s[42:43]
	s_mov_b32 m0, s49
	s_add_u32 s49, s48, 0xc00
	global_load_lds_dwordx4 v2, s[42:43]
	s_mov_b32 m0, s49
	s_nop 0
	global_load_lds_dwordx4 v3, s[42:43]
	s_branch .Lcv_rga_pj1
